# EpiRes/EpiMerge epilogues pipelined with counted waits; S5 U-prefetch; w_out sample-row reduce batches its 12 partial loads
# speedup vs baseline: 1.0565x; 1.0565x over previous
;     __device__ __forceinline__ void operator()(const f32x4 (&acc)[2][2][4][2], const Unit& u, int wr, int wc, int fr, int fq) const {
;         const float* gp = MODG + (size_t)(u.pm >> 3) * cfg::NMOD + u.pn * 256 + wc * 32 + 8 * fq;
;         f32x4 g[2][2];
; #pragma unroll
;         for (int bj = 0; bj < 2; ++bj)
; #pragma unroll
;             for (int n = 0; n < 2; ++n) g[bj][n] = *(const f32x4*)(gp + bj * 128 + n * 4);
; #pragma unroll
;         for (int ai = 0; ai < 2; ++ai)
; #pragma unroll
;             for (int m = 0; m < 4; ++m) { const int row = u.pm * 256 + ai * 128 + wr * 64 + m * 16 + fr;
; #pragma unroll
;                 for (int bj = 0; bj < 2; ++bj)
; #pragma unroll
;                     for (int n = 0; n < 2; ++n) { const size_t o = (size_t)row * 1024 + u.pn * 256 + bj * 128 + wc * 32 + 8 * fq + 4 * n;
;                         *(f32x4*)(X + o) = *(const f32x4*)(xin + o) + g[bj][n] * acc[ai][bj][m][n]; } }
.LBB0_252:
	s_ashr_i32 s9, s16, 3
	s_mul_hi_i32 s11, s9, 0x18000
	s_mul_i32 s9, s9, 0x18000
	s_add_u32 s9, s42, s9
	s_addc_u32 s11, s43, s11
	s_lshl_b32 s18, s17, 8
	s_ashr_i32 s19, s18, 31
	s_lshl_b64 s[20:21], s[18:19], 2
	s_add_u32 s9, s9, s20
	s_addc_u32 s11, s11, s21
	v_lshl_add_u32 v162, s16, 8, v164
	s_add_u32 s20, s9, s54
	v_ashrrev_i32_e32 v163, 31, v162
	s_addc_u32 s21, s11, 0
	s_or_b64 s[16:17], s[18:19], s[56:57]
	v_lshlrev_b64 v[130:131], 10, v[162:163]
	v_lshl_add_u64 v[130:131], v[130:131], 0, s[16:17]
	v_or_b32_e32 v130, v130, v96
	v_lshlrev_b64 v[146:147], 2, v[130:131]
	v_lshlrev_b32_e32 v134, 2, v96
	v_mov_b32_e32 v168, v146
	global_load_dwordx4 v[142:145], v134, s[20:21]
	global_load_dwordx4 v[138:141], v134, s[20:21] offset:16
	global_load_dwordx4 v[130:133], v134, s[20:21] offset:528
	s_nop 0
	global_load_dwordx4 v[134:137], v134, s[20:21] offset:512
	s_andn2_b64 vcc, exec, s[6:7]
	s_mov_b64 s[6:7], -1
	s_mov_b32 s75, 0x400000
	s_mov_b32 s74, 0x600000
	s_mov_b32 s73, 0xc00000
	v_add_u32_e32 v169, 0x10000, v168
	v_add_u32_e32 v170, 0x20000, v168
	v_add_u32_e32 v171, 0x30000, v168
	v_add_u32_e32 v172, 0x80000, v168
	v_add_u32_e32 v173, 0x90000, v168
	v_add_u32_e32 v174, 0xa0000, v168
	v_add_u32_e32 v175, 0xb0000, v168
	global_load_dwordx4 v[198:201], v168, s[84:85]
	global_load_dwordx4 v[202:205], v168, s[84:85] offset:16
	global_load_dwordx4 v[206:209], v168, s[84:85] offset:512
	global_load_dwordx4 v[210:213], v168, s[84:85] offset:528
	global_load_dwordx4 v[214:217], v169, s[84:85]
	global_load_dwordx4 v[218:221], v169, s[84:85] offset:16
	global_load_dwordx4 v[222:225], v169, s[84:85] offset:512
	global_load_dwordx4 v[226:229], v169, s[84:85] offset:528
	global_load_dwordx4 v[230:233], v170, s[84:85]
	global_load_dwordx4 v[234:237], v170, s[84:85] offset:16
	global_load_dwordx4 v[238:241], v170, s[84:85] offset:512
	global_load_dwordx4 v[242:245], v170, s[84:85] offset:528
	global_load_dwordx4 v[246:249], v171, s[84:85]
	global_load_dwordx4 v[250:253], v171, s[84:85] offset:16
	global_load_dwordx4 v[182:185], v171, s[84:85] offset:512
	global_load_dwordx4 v[186:189], v171, s[84:85] offset:528
	s_waitcnt vmcnt(12)
	v_pk_fma_f32 v[128:129], v[128:129], v[144:145], v[200:201]
	v_pk_fma_f32 v[126:127], v[126:127], v[142:143], v[198:199]
	v_pk_fma_f32 v[124:125], v[124:125], v[140:141], v[204:205]
	v_pk_fma_f32 v[122:123], v[122:123], v[138:139], v[202:203]
	v_pk_fma_f32 v[120:121], v[120:121], v[136:137], v[208:209]
	v_pk_fma_f32 v[118:119], v[118:119], v[134:135], v[206:207]
	v_pk_fma_f32 v[108:109], v[108:109], v[132:133], v[212:213]
	v_pk_fma_f32 v[106:107], v[106:107], v[130:131], v[210:211]
	global_store_dwordx4 v168, v[126:129], s[24:25]
	global_store_dwordx4 v168, v[122:125], s[24:25] offset:16
	global_store_dwordx4 v168, v[118:121], s[24:25] offset:512
	global_store_dwordx4 v168, v[106:109], s[24:25] offset:528
	global_load_dwordx4 v[198:201], v172, s[84:85]
	global_load_dwordx4 v[202:205], v172, s[84:85] offset:16
	global_load_dwordx4 v[206:209], v172, s[84:85] offset:512
	global_load_dwordx4 v[210:213], v172, s[84:85] offset:528
	s_waitcnt vmcnt(16)
	v_pk_fma_f32 v[116:117], v[116:117], v[144:145], v[216:217]
	v_pk_fma_f32 v[114:115], v[114:115], v[142:143], v[214:215]
	v_pk_fma_f32 v[112:113], v[112:113], v[140:141], v[220:221]
	v_pk_fma_f32 v[110:111], v[110:111], v[138:139], v[218:219]
	v_pk_fma_f32 v[104:105], v[104:105], v[136:137], v[224:225]
	v_pk_fma_f32 v[102:103], v[102:103], v[134:135], v[222:223]
	v_pk_fma_f32 v[90:91], v[90:91], v[132:133], v[228:229]
	v_pk_fma_f32 v[88:89], v[88:89], v[130:131], v[226:227]
	global_store_dwordx4 v169, v[114:117], s[24:25]
	global_store_dwordx4 v169, v[110:113], s[24:25] offset:16
	global_store_dwordx4 v169, v[102:105], s[24:25] offset:512
	global_store_dwordx4 v169, v[88:91], s[24:25] offset:528
	global_load_dwordx4 v[214:217], v173, s[84:85]
	global_load_dwordx4 v[218:221], v173, s[84:85] offset:16
	global_load_dwordx4 v[222:225], v173, s[84:85] offset:512
	global_load_dwordx4 v[226:229], v173, s[84:85] offset:528
	s_waitcnt vmcnt(20)
; #define PG8_BAR __builtin_amdgcn_s_barrier()
;     __device__ __forceinline__ void operator()(const f32x4 (&acc)[2][2][4][2], const Unit& u, int wr, int wc, int fr, int fq) const {
;     ...
; #pragma unroll
;         for (int ai = 0; ai < 2; ++ai)
; #pragma unroll
;             for (int m = 0; m < 4; ++m) { const int row = u.pm * 256 + ai * 128 + wr * 64 + m * 16 + fr;
; #pragma unroll
;                 for (int bj = 0; bj < 2; ++bj)
; #pragma unroll
;                     for (int n = 0; n < 2; ++n) { const size_t o = (size_t)row * 1024 + u.pn * 256 + bj * 128 + wc * 32 + 8 * fq + 4 * n;
;                         *(f32x4*)(X + o) = *(const f32x4*)(xin + o) + g[bj][n] * acc[ai][bj][m][n]; } }
; template <class Epi, class Sched, bool ALIGN_EPI = false, bool SP2 = false>
; __device__ __forceinline__ void gemm_phase(PG8_LAS unsigned char* lds, const Gemm g, const Sched& S, const Epi& E, const int tid_in) {
;     ...
;         if constexpr (!Epi::AFTER_DRAIN) { E(acc, cur, wr, wc, fr, fq); S.done(cur); }
;         if (!has_next) break;
; #pragma unroll
;         for (int a = 0; a < 2; ++a)
; #pragma unroll
;             for (int b = 0; b < 2; ++b)
; #pragma unroll
;                 for (int m = 0; m < 4; ++m)
; #pragma unroll
;                     for (int n = 0; n < 2; ++n) acc[a][b][m][n] = (f32x4){0.f, 0.f, 0.f, 0.f};
;         cur = nxt; cA = nA; cB = nB; ++ui;
;         if constexpr (ALIGN_EPI) { if (wr == 1) PG8_BAR; }
	v_pk_fma_f32 v[100:101], v[100:101], v[144:145], v[232:233]
	v_pk_fma_f32 v[98:99], v[98:99], v[142:143], v[230:231]
	v_pk_fma_f32 v[94:95], v[94:95], v[140:141], v[236:237]
	v_pk_fma_f32 v[92:93], v[92:93], v[138:139], v[234:235]
	v_pk_fma_f32 v[86:87], v[86:87], v[136:137], v[240:241]
	v_pk_fma_f32 v[84:85], v[84:85], v[134:135], v[238:239]
	v_pk_fma_f32 v[74:75], v[74:75], v[132:133], v[244:245]
	v_pk_fma_f32 v[72:73], v[72:73], v[130:131], v[242:243]
	global_store_dwordx4 v170, v[98:101], s[24:25]
	global_store_dwordx4 v170, v[92:95], s[24:25] offset:16
	global_store_dwordx4 v170, v[84:87], s[24:25] offset:512
	global_store_dwordx4 v170, v[72:75], s[24:25] offset:528
	global_load_dwordx4 v[230:233], v174, s[84:85]
	global_load_dwordx4 v[234:237], v174, s[84:85] offset:16
	global_load_dwordx4 v[238:241], v174, s[84:85] offset:512
	global_load_dwordx4 v[242:245], v174, s[84:85] offset:528
	s_waitcnt vmcnt(24)
	v_pk_fma_f32 v[82:83], v[82:83], v[144:145], v[248:249]
	v_pk_fma_f32 v[80:81], v[80:81], v[142:143], v[246:247]
	v_pk_fma_f32 v[78:79], v[78:79], v[140:141], v[252:253]
	v_pk_fma_f32 v[76:77], v[76:77], v[138:139], v[250:251]
	v_pk_fma_f32 v[70:71], v[70:71], v[136:137], v[184:185]
	v_pk_fma_f32 v[68:69], v[68:69], v[134:135], v[182:183]
	v_pk_fma_f32 v[66:67], v[66:67], v[132:133], v[188:189]
	v_pk_fma_f32 v[64:65], v[64:65], v[130:131], v[186:187]
	global_store_dwordx4 v171, v[80:83], s[24:25]
	global_store_dwordx4 v171, v[76:79], s[24:25] offset:16
	global_store_dwordx4 v171, v[68:71], s[24:25] offset:512
	global_store_dwordx4 v171, v[64:67], s[24:25] offset:528
	global_load_dwordx4 v[246:249], v175, s[84:85]
	global_load_dwordx4 v[250:253], v175, s[84:85] offset:16
	global_load_dwordx4 v[182:185], v175, s[84:85] offset:512
	global_load_dwordx4 v[186:189], v175, s[84:85] offset:528
	s_waitcnt vmcnt(24)
	v_pk_fma_f32 v[62:63], v[62:63], v[144:145], v[200:201]
	v_pk_fma_f32 v[60:61], v[60:61], v[142:143], v[198:199]
	v_pk_fma_f32 v[58:59], v[58:59], v[140:141], v[204:205]
	v_pk_fma_f32 v[56:57], v[56:57], v[138:139], v[202:203]
	v_pk_fma_f32 v[54:55], v[54:55], v[136:137], v[208:209]
	v_pk_fma_f32 v[52:53], v[52:53], v[134:135], v[206:207]
	v_pk_fma_f32 v[42:43], v[42:43], v[132:133], v[212:213]
	v_pk_fma_f32 v[40:41], v[40:41], v[130:131], v[210:211]
	global_store_dwordx4 v172, v[60:63], s[24:25]
	global_store_dwordx4 v172, v[56:59], s[24:25] offset:16
	global_store_dwordx4 v172, v[52:55], s[24:25] offset:512
	global_store_dwordx4 v172, v[40:43], s[24:25] offset:528
	s_waitcnt vmcnt(20)
	v_pk_fma_f32 v[50:51], v[50:51], v[144:145], v[216:217]
	v_pk_fma_f32 v[48:49], v[48:49], v[142:143], v[214:215]
	v_pk_fma_f32 v[46:47], v[46:47], v[140:141], v[220:221]
	v_pk_fma_f32 v[44:45], v[44:45], v[138:139], v[218:219]
	v_pk_fma_f32 v[38:39], v[38:39], v[136:137], v[224:225]
	v_pk_fma_f32 v[36:37], v[36:37], v[134:135], v[222:223]
	v_pk_fma_f32 v[26:27], v[26:27], v[132:133], v[228:229]
	v_pk_fma_f32 v[24:25], v[24:25], v[130:131], v[226:227]
	global_store_dwordx4 v173, v[48:51], s[24:25]
	global_store_dwordx4 v173, v[44:47], s[24:25] offset:16
	global_store_dwordx4 v173, v[36:39], s[24:25] offset:512
	global_store_dwordx4 v173, v[24:27], s[24:25] offset:528
	s_waitcnt vmcnt(16)
	v_pk_fma_f32 v[34:35], v[34:35], v[144:145], v[232:233]
	v_pk_fma_f32 v[32:33], v[32:33], v[142:143], v[230:231]
	v_pk_fma_f32 v[30:31], v[30:31], v[140:141], v[236:237]
	v_pk_fma_f32 v[28:29], v[28:29], v[138:139], v[234:235]
	v_pk_fma_f32 v[22:23], v[22:23], v[136:137], v[240:241]
	v_pk_fma_f32 v[20:21], v[20:21], v[134:135], v[238:239]
	v_pk_fma_f32 v[10:11], v[10:11], v[132:133], v[244:245]
	v_pk_fma_f32 v[8:9], v[8:9], v[130:131], v[242:243]
	global_store_dwordx4 v174, v[32:35], s[24:25]
	global_store_dwordx4 v174, v[28:31], s[24:25] offset:16
	global_store_dwordx4 v174, v[20:23], s[24:25] offset:512
	global_store_dwordx4 v174, v[8:11], s[24:25] offset:528
	s_waitcnt vmcnt(12)
	v_pk_fma_f32 v[18:19], v[18:19], v[144:145], v[248:249]
	v_pk_fma_f32 v[16:17], v[16:17], v[142:143], v[246:247]
	v_pk_fma_f32 v[14:15], v[14:15], v[140:141], v[252:253]
	v_pk_fma_f32 v[12:13], v[12:13], v[138:139], v[250:251]
	v_pk_fma_f32 v[6:7], v[6:7], v[136:137], v[184:185]
	v_pk_fma_f32 v[4:5], v[4:5], v[134:135], v[182:183]
	v_pk_fma_f32 v[2:3], v[2:3], v[132:133], v[188:189]
	v_pk_fma_f32 v[0:1], v[0:1], v[130:131], v[186:187]
	global_store_dwordx4 v175, v[16:19], s[24:25]
	global_store_dwordx4 v175, v[12:15], s[24:25] offset:16
	global_store_dwordx4 v175, v[4:7], s[24:25] offset:512
	global_store_dwordx4 v175, v[0:3], s[24:25] offset:528
	s_cbranch_vccnz .LBB0_241
	s_andn2_b64 vcc, exec, s[2:3]
	s_cbranch_vccnz .LBB0_240
	s_barrier
	s_branch .LBB0_240

; __device__ __forceinline__ int lane_id_v() { int l; asm volatile("v_mbcnt_lo_u32_b32 %0, -1, 0\n\tv_mbcnt_hi_u32_b32 %0, -1, %0" : "=v"(l)); return l; }
; __device__ __forceinline__ void st_bf4(bf16_t* p, const f32x4 v) { u32x2 w; w.x = cvt_pk_bf16(v[0], v[1]); w.y = cvt_pk_bf16(v[2], v[3]); *(u32x2*)p = w; }
; __global__ void __launch_bounds__(512, 2) mega(Args a_unused) {
;     ...
;                 for (int j = c; j < 64; j += G) { const int ks = j & 7, pmr = j >> 5; const float* Pm = (const float*)(ws + WS_Q);
;                     for (int e2 = wave_s * 64 + lane_id_v(); e2 < 256 * 32; e2 += 512) { const int rs = pmr * 256 + (e2 >> 5), c4 = ks * 128 + (e2 & 31) * 4; f32x4 s = {0.f, 0.f, 0.f, 0.f};
; #pragma unroll
;                         for (int p = 0; p < 12; ++p) s += *(const f32x4*)(Pm + ((size_t)p * 512 + rs) * 1024 + c4);
;                         st_bf4(H + (size_t)(MP + rs) * 1024 + c4, s); } }
.LBB0_261:
	v_ashrrev_i32_e32 v0, 5, v2
	v_and_b32_e32 v1, 0x7c, v3
	v_add_u32_e32 v0, s11, v0
	v_or_b32_e32 v14, s12, v1
	v_ashrrev_i32_e32 v1, 31, v0
	v_lshlrev_b32_e32 v96, 2, v14
	v_lshl_add_u64 v[4:5], s[4:5], 0, v[96:97]
	v_lshlrev_b64 v[6:7], 12, v[0:1]
	v_lshl_add_u64 v[8:9], v[4:5], 0, v[6:7]
	global_load_dwordx4 v[198:201], v[8:9], off
	v_add_co_u32_e32 v246, vcc, s97, v8
	s_nop 1
	v_addc_co_u32_e32 v247, vcc, 0, v9, vcc
	global_load_dwordx4 v[202:205], v[246:247], off
	v_add_co_u32_e32 v246, vcc, s75, v8
	s_nop 1
	v_addc_co_u32_e32 v247, vcc, 0, v9, vcc
	global_load_dwordx4 v[206:209], v[246:247], off
	v_add_co_u32_e32 v246, vcc, s74, v8
	s_nop 1
	v_addc_co_u32_e32 v247, vcc, 0, v9, vcc
	global_load_dwordx4 v[210:213], v[246:247], off
	v_add_co_u32_e32 v246, vcc, s42, v8
	s_nop 1
	v_addc_co_u32_e32 v247, vcc, 0, v9, vcc
	global_load_dwordx4 v[214:217], v[246:247], off
	v_add_co_u32_e32 v246, vcc, s72, v8
	s_nop 1
	v_addc_co_u32_e32 v247, vcc, 0, v9, vcc
	global_load_dwordx4 v[218:221], v[246:247], off
	v_add_co_u32_e32 v246, vcc, s73, v8
	s_nop 1
	v_addc_co_u32_e32 v247, vcc, 0, v9, vcc
	global_load_dwordx4 v[222:225], v[246:247], off
	v_add_co_u32_e32 v246, vcc, s46, v8
	s_nop 1
	v_addc_co_u32_e32 v247, vcc, 0, v9, vcc
	global_load_dwordx4 v[226:229], v[246:247], off
	v_add_co_u32_e32 v246, vcc, s60, v8
	s_nop 1
	v_addc_co_u32_e32 v247, vcc, 0, v9, vcc
	global_load_dwordx4 v[230:233], v[246:247], off
	v_add_co_u32_e32 v246, vcc, s70, v8
	s_nop 1
	v_addc_co_u32_e32 v247, vcc, 0, v9, vcc
	global_load_dwordx4 v[234:237], v[246:247], off
	v_add_co_u32_e32 v246, vcc, s71, v8
	s_nop 1
	v_addc_co_u32_e32 v247, vcc, 0, v9, vcc
	global_load_dwordx4 v[238:241], v[246:247], off
	v_add_co_u32_e32 v246, vcc, s14, v8
	s_nop 1
	v_addc_co_u32_e32 v247, vcc, 0, v9, vcc
	global_load_dwordx4 v[242:245], v[246:247], off
	v_lshlrev_b64 v[0:1], 11, v[0:1]
	v_lshl_add_u64 v[0:1], s[88:89], 0, v[0:1]
	v_lshlrev_b32_e32 v96, 1, v14
	v_lshl_add_u64 v[0:1], v[0:1], 0, v[96:97]
	s_movk_i32 s13, 0x1dff
	v_add_u32_e32 v3, 0x800, v3
	s_waitcnt vmcnt(11)
	v_pk_add_f32 v[12:13], v[198:199], 0 op_sel_hi:[1,0]
	v_pk_add_f32 v[10:11], v[200:201], 0 op_sel_hi:[1,0]
	s_waitcnt vmcnt(10)
	v_pk_add_f32 v[12:13], v[12:13], v[202:203]
	v_pk_add_f32 v[10:11], v[10:11], v[204:205]
	s_waitcnt vmcnt(9)
	v_pk_add_f32 v[12:13], v[12:13], v[206:207]
	v_pk_add_f32 v[10:11], v[10:11], v[208:209]
	s_waitcnt vmcnt(8)
	v_pk_add_f32 v[12:13], v[12:13], v[210:211]
	v_pk_add_f32 v[10:11], v[10:11], v[212:213]
	s_waitcnt vmcnt(7)
	v_pk_add_f32 v[12:13], v[12:13], v[214:215]
	v_pk_add_f32 v[10:11], v[10:11], v[216:217]
	s_waitcnt vmcnt(6)
	v_pk_add_f32 v[12:13], v[12:13], v[218:219]
	v_pk_add_f32 v[10:11], v[10:11], v[220:221]
	s_waitcnt vmcnt(5)
	v_pk_add_f32 v[12:13], v[12:13], v[222:223]
	v_pk_add_f32 v[10:11], v[10:11], v[224:225]
	s_waitcnt vmcnt(4)
	v_pk_add_f32 v[12:13], v[12:13], v[226:227]
	v_pk_add_f32 v[10:11], v[10:11], v[228:229]
	s_waitcnt vmcnt(3)
	v_pk_add_f32 v[12:13], v[12:13], v[230:231]
	v_pk_add_f32 v[10:11], v[10:11], v[232:233]
	s_waitcnt vmcnt(2)
	v_pk_add_f32 v[12:13], v[12:13], v[234:235]
	v_pk_add_f32 v[10:11], v[10:11], v[236:237]
	s_waitcnt vmcnt(1)
	v_pk_add_f32 v[12:13], v[12:13], v[238:239]
	v_pk_add_f32 v[10:11], v[10:11], v[240:241]
	v_add_co_u32_e32 v0, vcc, 0x2000000, v0
	s_waitcnt vmcnt(0)
	v_pk_add_f32 v[4:5], v[12:13], v[242:243]
	v_addc_co_u32_e32 v1, vcc, 0, v1, vcc
	v_pk_add_f32 v[6:7], v[10:11], v[244:245]
	v_cvt_pk_bf16_f32 v4, v4, v5
	v_cmp_lt_i32_e32 vcc, s13, v2
	v_cvt_pk_bf16_f32 v5, v6, v7
	global_store_dwordx2 v[0:1], v[4:5], off
	v_add_u32_e32 v0, 0x200, v2
	s_or_b64 s[8:9], vcc, s[8:9]
	v_mov_b32_e32 v2, v0
	s_andn2_b64 exec, exec, s[8:9]
	s_cbranch_execnz .LBB0_261
	s_branch .LBB0_258

; __device__ __forceinline__ f32x4 ld_bf4(const bf16_t* p) { const u32x2 w = *(const u32x2*)p; f32x4 r; r[0] = __uint_as_float(w.x << 16); r[1] = __uint_as_float(w.x & 0xffff0000u); r[2] = __uint_as_float(w.y << 16); r[3] = __uint_as_float(w.y & 0xffff0000u); return r; }
; __device__ __forceinline__ void st_bf4(bf16_t* p, const f32x4 v) { u32x2 w; w.x = cvt_pk_bf16(v[0], v[1]); w.y = cvt_pk_bf16(v[2], v[3]); *(u32x2*)p = w; }
;     __device__ __forceinline__ void operator()(const f32x4 (&acc)[2][2][4][2], const Unit& u, int wr, int wc, int fr, int fq) const {
;         const int br = u.pm / 66, pm = u.pm - br * 66, pn = u.pn & 3;
;         if (br > 0) asm volatile("s_waitcnt vmcnt(0)" ::: "memory");
; #pragma unroll
;         for (int ai = 0; ai < 2; ++ai)
; #pragma unroll
;             for (int m = 0; m < 4; ++m) { const int row = pm * 256 + ai * 128 + wr * 64 + m * 16 + fr;
; #pragma unroll
;                 for (int bj = 0; bj < 2; ++bj)
; #pragma unroll
;                     for (int n = 0; n < 2; ++n) { const int col = pn * 256 + bj * 128 + wc * 32 + 8 * fq + 4 * n; const f32x4 v = acc[ai][bj][m][n];
;                         const f32x4 g = ld_bf4(GT + (size_t)row * 3072 + br * 1024 + col);
;                         bf16_t* mp = M16 + (size_t)row * 1024 + col;
;                         if (br == 0) st_bf4(mp, g * v); else st_bf4(mp, ld_bf4(mp) + g * v); } }
.LBB0_298:
	s_mul_hi_i32 s7, s6, 0x3e0f83e1
	s_lshr_b32 s11, s7, 31
	s_ashr_i32 s7, s7, 4
	s_add_i32 s7, s7, s11
	s_mul_i32 s11, s7, 0xffffffbe
	s_add_i32 s11, s11, s6
	v_lshl_add_u32 v142, s11, 8, v158
	s_lshl_b32 s11, s55, 8
	s_lshl_b32 s20, s7, 10
	s_and_b32 s11, s11, 0x300
	s_addk_i32 s6, 0x41
	v_or_b32_e32 v96, s11, v160
	s_cmpk_gt_u32 s6, 0x82
	v_lshlrev_b32_e32 v96, 1, v96
	s_cselect_b64 s[22:23], -1, 0
	v_mul_u32_u24_e32 v170, s61, v142
	v_add_u32_e32 v170, v170, v96
	v_lshl_add_u32 v170, s20, 1, v170
	v_lshl_add_u32 v186, v142, 11, v96
	v_add_u32_e32 v171, 0x18000, v170
	v_add_u32_e32 v187, 0x8000, v186
	v_add_u32_e32 v172, 0x30000, v170
	v_add_u32_e32 v188, 0x10000, v186
	v_add_u32_e32 v173, 0x48000, v170
	v_add_u32_e32 v189, 0x18000, v186
	v_add_u32_e32 v174, 0xc0000, v170
	v_add_u32_e32 v190, 0x40000, v186
	v_add_u32_e32 v175, 0xd8000, v170
	v_add_u32_e32 v191, 0x48000, v186
	v_add_u32_e32 v176, 0xf0000, v170
	v_add_u32_e32 v192, 0x50000, v186
	v_add_u32_e32 v177, 0x108000, v170
	v_add_u32_e32 v193, 0x58000, v186
	s_mov_b32 s74, 0x600000
	s_mov_b32 s72, 0xa00000
	s_mov_b32 s73, 0xc00000
	s_and_b64 vcc, exec, s[22:23]
	s_cbranch_vccz .Lem_first
	global_load_dwordx4 v[198:201], v170, s[2:3]
	global_load_dwordx4 v[202:205], v170, s[2:3] offset:256
	global_load_dwordx4 v[206:209], v186, s[88:89]
	global_load_dwordx4 v[210:213], v186, s[88:89] offset:256
	global_load_dwordx4 v[214:217], v171, s[2:3]
	global_load_dwordx4 v[218:221], v171, s[2:3] offset:256
	global_load_dwordx4 v[222:225], v187, s[88:89]
	global_load_dwordx4 v[226:229], v187, s[88:89] offset:256
	global_load_dwordx4 v[230:233], v172, s[2:3]
	global_load_dwordx4 v[234:237], v172, s[2:3] offset:256
	global_load_dwordx4 v[238:241], v188, s[88:89]
	global_load_dwordx4 v[242:245], v188, s[88:89] offset:256
	global_load_dwordx4 v[246:249], v173, s[2:3]
	global_load_dwordx4 v[250:253], v173, s[2:3] offset:256
	global_load_dwordx4 v[182:185], v189, s[88:89]
	global_load_dwordx4 v[150:153], v189, s[88:89] offset:256
	s_waitcnt vmcnt(12)
	v_lshlrev_b32_e32 v142, 16, v198
	v_and_b32_e32 v143, 0xffff0000, v198
	v_lshlrev_b32_e32 v144, 16, v199
	v_and_b32_e32 v145, 0xffff0000, v199
	v_lshlrev_b32_e32 v146, 16, v206
	v_and_b32_e32 v147, 0xffff0000, v206
	v_lshlrev_b32_e32 v148, 16, v207
	v_and_b32_e32 v149, 0xffff0000, v207
	v_pk_fma_f32 v[128:129], v[128:129], v[144:145], v[148:149]
	v_pk_fma_f32 v[126:127], v[126:127], v[142:143], v[146:147]
	v_cvt_pk_bf16_f32 v206, v126, v127
	v_cvt_pk_bf16_f32 v207, v128, v129
	v_lshlrev_b32_e32 v142, 16, v200
	v_and_b32_e32 v143, 0xffff0000, v200
	v_lshlrev_b32_e32 v144, 16, v201
	v_and_b32_e32 v145, 0xffff0000, v201
	v_lshlrev_b32_e32 v146, 16, v208
	v_and_b32_e32 v147, 0xffff0000, v208
	v_lshlrev_b32_e32 v148, 16, v209
	v_and_b32_e32 v149, 0xffff0000, v209
	v_pk_fma_f32 v[124:125], v[124:125], v[144:145], v[148:149]
	v_pk_fma_f32 v[122:123], v[122:123], v[142:143], v[146:147]
	v_cvt_pk_bf16_f32 v208, v122, v123
	v_cvt_pk_bf16_f32 v209, v124, v125
	v_lshlrev_b32_e32 v142, 16, v202
	v_and_b32_e32 v143, 0xffff0000, v202
	v_lshlrev_b32_e32 v144, 16, v203
	v_and_b32_e32 v145, 0xffff0000, v203
	v_lshlrev_b32_e32 v146, 16, v210
	v_and_b32_e32 v147, 0xffff0000, v210
	v_lshlrev_b32_e32 v148, 16, v211
	v_and_b32_e32 v149, 0xffff0000, v211
	v_pk_fma_f32 v[120:121], v[120:121], v[144:145], v[148:149]
	v_pk_fma_f32 v[118:119], v[118:119], v[142:143], v[146:147]
	v_cvt_pk_bf16_f32 v210, v118, v119
	v_cvt_pk_bf16_f32 v211, v120, v121
	v_lshlrev_b32_e32 v142, 16, v204
	v_and_b32_e32 v143, 0xffff0000, v204
	v_lshlrev_b32_e32 v144, 16, v205
	v_and_b32_e32 v145, 0xffff0000, v205
	v_lshlrev_b32_e32 v146, 16, v212
	v_and_b32_e32 v147, 0xffff0000, v212
	v_lshlrev_b32_e32 v148, 16, v213
	v_and_b32_e32 v149, 0xffff0000, v213
	v_pk_fma_f32 v[116:117], v[116:117], v[144:145], v[148:149]
	v_pk_fma_f32 v[114:115], v[114:115], v[142:143], v[146:147]
	v_cvt_pk_bf16_f32 v212, v114, v115
	v_cvt_pk_bf16_f32 v213, v116, v117
	global_store_dwordx4 v186, v[206:209], s[88:89]
	global_store_dwordx4 v186, v[210:213], s[88:89] offset:256
	global_load_dwordx4 v[198:201], v174, s[2:3]
	global_load_dwordx4 v[202:205], v174, s[2:3] offset:256
	global_load_dwordx4 v[206:209], v190, s[88:89]
	global_load_dwordx4 v[210:213], v190, s[88:89] offset:256
	s_waitcnt vmcnt(14)
	v_lshlrev_b32_e32 v142, 16, v214
	v_and_b32_e32 v143, 0xffff0000, v214
	v_lshlrev_b32_e32 v144, 16, v215
	v_and_b32_e32 v145, 0xffff0000, v215
	v_lshlrev_b32_e32 v146, 16, v222
	v_and_b32_e32 v147, 0xffff0000, v222
	v_lshlrev_b32_e32 v148, 16, v223
	v_and_b32_e32 v149, 0xffff0000, v223
	v_pk_fma_f32 v[112:113], v[112:113], v[144:145], v[148:149]
	v_pk_fma_f32 v[110:111], v[110:111], v[142:143], v[146:147]
	v_cvt_pk_bf16_f32 v222, v110, v111
	v_cvt_pk_bf16_f32 v223, v112, v113
	v_lshlrev_b32_e32 v142, 16, v216
	v_and_b32_e32 v143, 0xffff0000, v216
	v_lshlrev_b32_e32 v144, 16, v217
	v_and_b32_e32 v145, 0xffff0000, v217
	v_lshlrev_b32_e32 v146, 16, v224
	v_and_b32_e32 v147, 0xffff0000, v224
	v_lshlrev_b32_e32 v148, 16, v225
	v_and_b32_e32 v149, 0xffff0000, v225
	v_pk_fma_f32 v[108:109], v[108:109], v[144:145], v[148:149]
	v_pk_fma_f32 v[106:107], v[106:107], v[142:143], v[146:147]
	v_cvt_pk_bf16_f32 v224, v106, v107
	v_cvt_pk_bf16_f32 v225, v108, v109
	v_lshlrev_b32_e32 v142, 16, v218
	v_and_b32_e32 v143, 0xffff0000, v218
	v_lshlrev_b32_e32 v144, 16, v219
	v_and_b32_e32 v145, 0xffff0000, v219
	v_lshlrev_b32_e32 v146, 16, v226
	v_and_b32_e32 v147, 0xffff0000, v226
	v_lshlrev_b32_e32 v148, 16, v227
	v_and_b32_e32 v149, 0xffff0000, v227
	v_pk_fma_f32 v[104:105], v[104:105], v[144:145], v[148:149]
	v_pk_fma_f32 v[102:103], v[102:103], v[142:143], v[146:147]
	v_cvt_pk_bf16_f32 v226, v102, v103
	v_cvt_pk_bf16_f32 v227, v104, v105
	v_lshlrev_b32_e32 v142, 16, v220
	v_and_b32_e32 v143, 0xffff0000, v220
	v_lshlrev_b32_e32 v144, 16, v221
	v_and_b32_e32 v145, 0xffff0000, v221
	v_lshlrev_b32_e32 v146, 16, v228
	v_and_b32_e32 v147, 0xffff0000, v228
	v_lshlrev_b32_e32 v148, 16, v229
	v_and_b32_e32 v149, 0xffff0000, v229
	v_pk_fma_f32 v[100:101], v[100:101], v[144:145], v[148:149]
	v_pk_fma_f32 v[98:99], v[98:99], v[142:143], v[146:147]
	v_cvt_pk_bf16_f32 v228, v98, v99
	v_cvt_pk_bf16_f32 v229, v100, v101
	global_store_dwordx4 v187, v[222:225], s[88:89]
	global_store_dwordx4 v187, v[226:229], s[88:89] offset:256
	global_load_dwordx4 v[214:217], v175, s[2:3]
	global_load_dwordx4 v[218:221], v175, s[2:3] offset:256
	global_load_dwordx4 v[222:225], v191, s[88:89]
	global_load_dwordx4 v[226:229], v191, s[88:89] offset:256
	s_waitcnt vmcnt(16)
; __device__ __forceinline__ f32x4 ld_bf4(const bf16_t* p) { const u32x2 w = *(const u32x2*)p; f32x4 r; r[0] = __uint_as_float(w.x << 16); r[1] = __uint_as_float(w.x & 0xffff0000u); r[2] = __uint_as_float(w.y << 16); r[3] = __uint_as_float(w.y & 0xffff0000u); return r; }
; __device__ __forceinline__ void st_bf4(bf16_t* p, const f32x4 v) { u32x2 w; w.x = cvt_pk_bf16(v[0], v[1]); w.y = cvt_pk_bf16(v[2], v[3]); *(u32x2*)p = w; }
;     __device__ __forceinline__ void operator()(const f32x4 (&acc)[2][2][4][2], const Unit& u, int wr, int wc, int fr, int fq) const {
;     ...
;         for (int ai = 0; ai < 2; ++ai)
; #pragma unroll
;             for (int m = 0; m < 4; ++m) { const int row = pm * 256 + ai * 128 + wr * 64 + m * 16 + fr;
; #pragma unroll
;                 for (int bj = 0; bj < 2; ++bj)
; #pragma unroll
;                     for (int n = 0; n < 2; ++n) { const int col = pn * 256 + bj * 128 + wc * 32 + 8 * fq + 4 * n; const f32x4 v = acc[ai][bj][m][n];
;                         const f32x4 g = ld_bf4(GT + (size_t)row * 3072 + br * 1024 + col);
;                         bf16_t* mp = M16 + (size_t)row * 1024 + col;
;                         if (br == 0) st_bf4(mp, g * v); else st_bf4(mp, ld_bf4(mp) + g * v); } }
	v_lshlrev_b32_e32 v142, 16, v230
	v_and_b32_e32 v143, 0xffff0000, v230
	v_lshlrev_b32_e32 v144, 16, v231
	v_and_b32_e32 v145, 0xffff0000, v231
	v_lshlrev_b32_e32 v146, 16, v238
	v_and_b32_e32 v147, 0xffff0000, v238
	v_lshlrev_b32_e32 v148, 16, v239
	v_and_b32_e32 v149, 0xffff0000, v239
	v_pk_fma_f32 v[94:95], v[94:95], v[144:145], v[148:149]
	v_pk_fma_f32 v[92:93], v[92:93], v[142:143], v[146:147]
	v_cvt_pk_bf16_f32 v238, v92, v93
	v_cvt_pk_bf16_f32 v239, v94, v95
	v_lshlrev_b32_e32 v142, 16, v232
	v_and_b32_e32 v143, 0xffff0000, v232
	v_lshlrev_b32_e32 v144, 16, v233
	v_and_b32_e32 v145, 0xffff0000, v233
	v_lshlrev_b32_e32 v146, 16, v240
	v_and_b32_e32 v147, 0xffff0000, v240
	v_lshlrev_b32_e32 v148, 16, v241
	v_and_b32_e32 v149, 0xffff0000, v241
	v_pk_fma_f32 v[90:91], v[90:91], v[144:145], v[148:149]
	v_pk_fma_f32 v[88:89], v[88:89], v[142:143], v[146:147]
	v_cvt_pk_bf16_f32 v240, v88, v89
	v_cvt_pk_bf16_f32 v241, v90, v91
	v_lshlrev_b32_e32 v142, 16, v234
	v_and_b32_e32 v143, 0xffff0000, v234
	v_lshlrev_b32_e32 v144, 16, v235
	v_and_b32_e32 v145, 0xffff0000, v235
	v_lshlrev_b32_e32 v146, 16, v242
	v_and_b32_e32 v147, 0xffff0000, v242
	v_lshlrev_b32_e32 v148, 16, v243
	v_and_b32_e32 v149, 0xffff0000, v243
	v_pk_fma_f32 v[86:87], v[86:87], v[144:145], v[148:149]
	v_pk_fma_f32 v[84:85], v[84:85], v[142:143], v[146:147]
	v_cvt_pk_bf16_f32 v242, v84, v85
	v_cvt_pk_bf16_f32 v243, v86, v87
	v_lshlrev_b32_e32 v142, 16, v236
	v_and_b32_e32 v143, 0xffff0000, v236
	v_lshlrev_b32_e32 v144, 16, v237
	v_and_b32_e32 v145, 0xffff0000, v237
	v_lshlrev_b32_e32 v146, 16, v244
	v_and_b32_e32 v147, 0xffff0000, v244
	v_lshlrev_b32_e32 v148, 16, v245
	v_and_b32_e32 v149, 0xffff0000, v245
	v_pk_fma_f32 v[82:83], v[82:83], v[144:145], v[148:149]
	v_pk_fma_f32 v[80:81], v[80:81], v[142:143], v[146:147]
	v_cvt_pk_bf16_f32 v244, v80, v81
	v_cvt_pk_bf16_f32 v245, v82, v83
	global_store_dwordx4 v188, v[238:241], s[88:89]
	global_store_dwordx4 v188, v[242:245], s[88:89] offset:256
	global_load_dwordx4 v[230:233], v176, s[2:3]
	global_load_dwordx4 v[234:237], v176, s[2:3] offset:256
	global_load_dwordx4 v[238:241], v192, s[88:89]
	global_load_dwordx4 v[242:245], v192, s[88:89] offset:256
	s_waitcnt vmcnt(18)
	v_lshlrev_b32_e32 v142, 16, v246
	v_and_b32_e32 v143, 0xffff0000, v246
	v_lshlrev_b32_e32 v144, 16, v247
	v_and_b32_e32 v145, 0xffff0000, v247
	v_lshlrev_b32_e32 v146, 16, v182
	v_and_b32_e32 v147, 0xffff0000, v182
	v_lshlrev_b32_e32 v148, 16, v183
	v_and_b32_e32 v149, 0xffff0000, v183
	v_pk_fma_f32 v[78:79], v[78:79], v[144:145], v[148:149]
	v_pk_fma_f32 v[76:77], v[76:77], v[142:143], v[146:147]
	v_cvt_pk_bf16_f32 v182, v76, v77
	v_cvt_pk_bf16_f32 v183, v78, v79
	v_lshlrev_b32_e32 v142, 16, v248
	v_and_b32_e32 v143, 0xffff0000, v248
	v_lshlrev_b32_e32 v144, 16, v249
	v_and_b32_e32 v145, 0xffff0000, v249
	v_lshlrev_b32_e32 v146, 16, v184
	v_and_b32_e32 v147, 0xffff0000, v184
	v_lshlrev_b32_e32 v148, 16, v185
	v_and_b32_e32 v149, 0xffff0000, v185
	v_pk_fma_f32 v[74:75], v[74:75], v[144:145], v[148:149]
	v_pk_fma_f32 v[72:73], v[72:73], v[142:143], v[146:147]
	v_cvt_pk_bf16_f32 v184, v72, v73
	v_cvt_pk_bf16_f32 v185, v74, v75
	v_lshlrev_b32_e32 v142, 16, v250
	v_and_b32_e32 v143, 0xffff0000, v250
	v_lshlrev_b32_e32 v144, 16, v251
	v_and_b32_e32 v145, 0xffff0000, v251
	v_lshlrev_b32_e32 v146, 16, v150
	v_and_b32_e32 v147, 0xffff0000, v150
	v_lshlrev_b32_e32 v148, 16, v151
	v_and_b32_e32 v149, 0xffff0000, v151
	v_pk_fma_f32 v[70:71], v[70:71], v[144:145], v[148:149]
	v_pk_fma_f32 v[68:69], v[68:69], v[142:143], v[146:147]
	v_cvt_pk_bf16_f32 v150, v68, v69
	v_cvt_pk_bf16_f32 v151, v70, v71
	v_lshlrev_b32_e32 v142, 16, v252
	v_and_b32_e32 v143, 0xffff0000, v252
	v_lshlrev_b32_e32 v144, 16, v253
	v_and_b32_e32 v145, 0xffff0000, v253
	v_lshlrev_b32_e32 v146, 16, v152
	v_and_b32_e32 v147, 0xffff0000, v152
	v_lshlrev_b32_e32 v148, 16, v153
	v_and_b32_e32 v149, 0xffff0000, v153
	v_pk_fma_f32 v[66:67], v[66:67], v[144:145], v[148:149]
	v_pk_fma_f32 v[64:65], v[64:65], v[142:143], v[146:147]
	v_cvt_pk_bf16_f32 v152, v64, v65
	v_cvt_pk_bf16_f32 v153, v66, v67
	global_store_dwordx4 v189, v[182:185], s[88:89]
	global_store_dwordx4 v189, v[150:153], s[88:89] offset:256
	global_load_dwordx4 v[246:249], v177, s[2:3]
	global_load_dwordx4 v[250:253], v177, s[2:3] offset:256
	global_load_dwordx4 v[182:185], v193, s[88:89]
	global_load_dwordx4 v[150:153], v193, s[88:89] offset:256
	s_waitcnt vmcnt(18)
	v_lshlrev_b32_e32 v142, 16, v198
	v_and_b32_e32 v143, 0xffff0000, v198
	v_lshlrev_b32_e32 v144, 16, v199
	v_and_b32_e32 v145, 0xffff0000, v199
	v_lshlrev_b32_e32 v146, 16, v206
	v_and_b32_e32 v147, 0xffff0000, v206
	v_lshlrev_b32_e32 v148, 16, v207
	v_and_b32_e32 v149, 0xffff0000, v207
	v_pk_fma_f32 v[62:63], v[62:63], v[144:145], v[148:149]
	v_pk_fma_f32 v[60:61], v[60:61], v[142:143], v[146:147]
	v_cvt_pk_bf16_f32 v206, v60, v61
	v_cvt_pk_bf16_f32 v207, v62, v63
	v_lshlrev_b32_e32 v142, 16, v200
	v_and_b32_e32 v143, 0xffff0000, v200
	v_lshlrev_b32_e32 v144, 16, v201
	v_and_b32_e32 v145, 0xffff0000, v201
	v_lshlrev_b32_e32 v146, 16, v208
	v_and_b32_e32 v147, 0xffff0000, v208
	v_lshlrev_b32_e32 v148, 16, v209
	v_and_b32_e32 v149, 0xffff0000, v209
	v_pk_fma_f32 v[58:59], v[58:59], v[144:145], v[148:149]
	v_pk_fma_f32 v[56:57], v[56:57], v[142:143], v[146:147]
	v_cvt_pk_bf16_f32 v208, v56, v57
	v_cvt_pk_bf16_f32 v209, v58, v59
	v_lshlrev_b32_e32 v142, 16, v202
	v_and_b32_e32 v143, 0xffff0000, v202
	v_lshlrev_b32_e32 v144, 16, v203
	v_and_b32_e32 v145, 0xffff0000, v203
	v_lshlrev_b32_e32 v146, 16, v210
	v_and_b32_e32 v147, 0xffff0000, v210
	v_lshlrev_b32_e32 v148, 16, v211
	v_and_b32_e32 v149, 0xffff0000, v211
	v_pk_fma_f32 v[54:55], v[54:55], v[144:145], v[148:149]
	v_pk_fma_f32 v[52:53], v[52:53], v[142:143], v[146:147]
	v_cvt_pk_bf16_f32 v210, v52, v53
	v_cvt_pk_bf16_f32 v211, v54, v55
	v_lshlrev_b32_e32 v142, 16, v204
	v_and_b32_e32 v143, 0xffff0000, v204
	v_lshlrev_b32_e32 v144, 16, v205
	v_and_b32_e32 v145, 0xffff0000, v205
	v_lshlrev_b32_e32 v146, 16, v212
	v_and_b32_e32 v147, 0xffff0000, v212
	v_lshlrev_b32_e32 v148, 16, v213
	v_and_b32_e32 v149, 0xffff0000, v213
	v_pk_fma_f32 v[50:51], v[50:51], v[144:145], v[148:149]
	v_pk_fma_f32 v[48:49], v[48:49], v[142:143], v[146:147]
	v_cvt_pk_bf16_f32 v212, v48, v49
	v_cvt_pk_bf16_f32 v213, v50, v51
	global_store_dwordx4 v190, v[206:209], s[88:89]
	global_store_dwordx4 v190, v[210:213], s[88:89] offset:256
	s_waitcnt vmcnt(14)
; __device__ __forceinline__ f32x4 ld_bf4(const bf16_t* p) { const u32x2 w = *(const u32x2*)p; f32x4 r; r[0] = __uint_as_float(w.x << 16); r[1] = __uint_as_float(w.x & 0xffff0000u); r[2] = __uint_as_float(w.y << 16); r[3] = __uint_as_float(w.y & 0xffff0000u); return r; }
; __device__ __forceinline__ void st_bf4(bf16_t* p, const f32x4 v) { u32x2 w; w.x = cvt_pk_bf16(v[0], v[1]); w.y = cvt_pk_bf16(v[2], v[3]); *(u32x2*)p = w; }
;     __device__ __forceinline__ void operator()(const f32x4 (&acc)[2][2][4][2], const Unit& u, int wr, int wc, int fr, int fq) const {
;     ...
;         for (int ai = 0; ai < 2; ++ai)
; #pragma unroll
;             for (int m = 0; m < 4; ++m) { const int row = pm * 256 + ai * 128 + wr * 64 + m * 16 + fr;
; #pragma unroll
;                 for (int bj = 0; bj < 2; ++bj)
; #pragma unroll
;                     for (int n = 0; n < 2; ++n) { const int col = pn * 256 + bj * 128 + wc * 32 + 8 * fq + 4 * n; const f32x4 v = acc[ai][bj][m][n];
;                         const f32x4 g = ld_bf4(GT + (size_t)row * 3072 + br * 1024 + col);
;                         bf16_t* mp = M16 + (size_t)row * 1024 + col;
;                         if (br == 0) st_bf4(mp, g * v); else st_bf4(mp, ld_bf4(mp) + g * v); } }
	v_lshlrev_b32_e32 v142, 16, v214
	v_and_b32_e32 v143, 0xffff0000, v214
	v_lshlrev_b32_e32 v144, 16, v215
	v_and_b32_e32 v145, 0xffff0000, v215
	v_lshlrev_b32_e32 v146, 16, v222
	v_and_b32_e32 v147, 0xffff0000, v222
	v_lshlrev_b32_e32 v148, 16, v223
	v_and_b32_e32 v149, 0xffff0000, v223
	v_pk_fma_f32 v[46:47], v[46:47], v[144:145], v[148:149]
	v_pk_fma_f32 v[44:45], v[44:45], v[142:143], v[146:147]
	v_cvt_pk_bf16_f32 v222, v44, v45
	v_cvt_pk_bf16_f32 v223, v46, v47
	v_lshlrev_b32_e32 v142, 16, v216
	v_and_b32_e32 v143, 0xffff0000, v216
	v_lshlrev_b32_e32 v144, 16, v217
	v_and_b32_e32 v145, 0xffff0000, v217
	v_lshlrev_b32_e32 v146, 16, v224
	v_and_b32_e32 v147, 0xffff0000, v224
	v_lshlrev_b32_e32 v148, 16, v225
	v_and_b32_e32 v149, 0xffff0000, v225
	v_pk_fma_f32 v[42:43], v[42:43], v[144:145], v[148:149]
	v_pk_fma_f32 v[40:41], v[40:41], v[142:143], v[146:147]
	v_cvt_pk_bf16_f32 v224, v40, v41
	v_cvt_pk_bf16_f32 v225, v42, v43
	v_lshlrev_b32_e32 v142, 16, v218
	v_and_b32_e32 v143, 0xffff0000, v218
	v_lshlrev_b32_e32 v144, 16, v219
	v_and_b32_e32 v145, 0xffff0000, v219
	v_lshlrev_b32_e32 v146, 16, v226
	v_and_b32_e32 v147, 0xffff0000, v226
	v_lshlrev_b32_e32 v148, 16, v227
	v_and_b32_e32 v149, 0xffff0000, v227
	v_pk_fma_f32 v[38:39], v[38:39], v[144:145], v[148:149]
	v_pk_fma_f32 v[36:37], v[36:37], v[142:143], v[146:147]
	v_cvt_pk_bf16_f32 v226, v36, v37
	v_cvt_pk_bf16_f32 v227, v38, v39
	v_lshlrev_b32_e32 v142, 16, v220
	v_and_b32_e32 v143, 0xffff0000, v220
	v_lshlrev_b32_e32 v144, 16, v221
	v_and_b32_e32 v145, 0xffff0000, v221
	v_lshlrev_b32_e32 v146, 16, v228
	v_and_b32_e32 v147, 0xffff0000, v228
	v_lshlrev_b32_e32 v148, 16, v229
	v_and_b32_e32 v149, 0xffff0000, v229
	v_pk_fma_f32 v[34:35], v[34:35], v[144:145], v[148:149]
	v_pk_fma_f32 v[32:33], v[32:33], v[142:143], v[146:147]
	v_cvt_pk_bf16_f32 v228, v32, v33
	v_cvt_pk_bf16_f32 v229, v34, v35
	global_store_dwordx4 v191, v[222:225], s[88:89]
	global_store_dwordx4 v191, v[226:229], s[88:89] offset:256
	s_waitcnt vmcnt(10)
	v_lshlrev_b32_e32 v142, 16, v230
	v_and_b32_e32 v143, 0xffff0000, v230
	v_lshlrev_b32_e32 v144, 16, v231
	v_and_b32_e32 v145, 0xffff0000, v231
	v_lshlrev_b32_e32 v146, 16, v238
	v_and_b32_e32 v147, 0xffff0000, v238
	v_lshlrev_b32_e32 v148, 16, v239
	v_and_b32_e32 v149, 0xffff0000, v239
	v_pk_fma_f32 v[30:31], v[30:31], v[144:145], v[148:149]
	v_pk_fma_f32 v[28:29], v[28:29], v[142:143], v[146:147]
	v_cvt_pk_bf16_f32 v238, v28, v29
	v_cvt_pk_bf16_f32 v239, v30, v31
	v_lshlrev_b32_e32 v142, 16, v232
	v_and_b32_e32 v143, 0xffff0000, v232
	v_lshlrev_b32_e32 v144, 16, v233
	v_and_b32_e32 v145, 0xffff0000, v233
	v_lshlrev_b32_e32 v146, 16, v240
	v_and_b32_e32 v147, 0xffff0000, v240
	v_lshlrev_b32_e32 v148, 16, v241
	v_and_b32_e32 v149, 0xffff0000, v241
	v_pk_fma_f32 v[26:27], v[26:27], v[144:145], v[148:149]
	v_pk_fma_f32 v[24:25], v[24:25], v[142:143], v[146:147]
	v_cvt_pk_bf16_f32 v240, v24, v25
	v_cvt_pk_bf16_f32 v241, v26, v27
	v_lshlrev_b32_e32 v142, 16, v234
	v_and_b32_e32 v143, 0xffff0000, v234
	v_lshlrev_b32_e32 v144, 16, v235
	v_and_b32_e32 v145, 0xffff0000, v235
	v_lshlrev_b32_e32 v146, 16, v242
	v_and_b32_e32 v147, 0xffff0000, v242
	v_lshlrev_b32_e32 v148, 16, v243
	v_and_b32_e32 v149, 0xffff0000, v243
	v_pk_fma_f32 v[22:23], v[22:23], v[144:145], v[148:149]
	v_pk_fma_f32 v[20:21], v[20:21], v[142:143], v[146:147]
	v_cvt_pk_bf16_f32 v242, v20, v21
	v_cvt_pk_bf16_f32 v243, v22, v23
	v_lshlrev_b32_e32 v142, 16, v236
	v_and_b32_e32 v143, 0xffff0000, v236
	v_lshlrev_b32_e32 v144, 16, v237
	v_and_b32_e32 v145, 0xffff0000, v237
	v_lshlrev_b32_e32 v146, 16, v244
	v_and_b32_e32 v147, 0xffff0000, v244
	v_lshlrev_b32_e32 v148, 16, v245
	v_and_b32_e32 v149, 0xffff0000, v245
	v_pk_fma_f32 v[18:19], v[18:19], v[144:145], v[148:149]
	v_pk_fma_f32 v[16:17], v[16:17], v[142:143], v[146:147]
	v_cvt_pk_bf16_f32 v244, v16, v17
	v_cvt_pk_bf16_f32 v245, v18, v19
	global_store_dwordx4 v192, v[238:241], s[88:89]
	global_store_dwordx4 v192, v[242:245], s[88:89] offset:256
	s_waitcnt vmcnt(6)
	v_lshlrev_b32_e32 v142, 16, v246
	v_and_b32_e32 v143, 0xffff0000, v246
	v_lshlrev_b32_e32 v144, 16, v247
	v_and_b32_e32 v145, 0xffff0000, v247
	v_lshlrev_b32_e32 v146, 16, v182
	v_and_b32_e32 v147, 0xffff0000, v182
	v_lshlrev_b32_e32 v148, 16, v183
	v_and_b32_e32 v149, 0xffff0000, v183
	v_pk_fma_f32 v[14:15], v[14:15], v[144:145], v[148:149]
	v_pk_fma_f32 v[12:13], v[12:13], v[142:143], v[146:147]
	v_cvt_pk_bf16_f32 v182, v12, v13
	v_cvt_pk_bf16_f32 v183, v14, v15
	v_lshlrev_b32_e32 v142, 16, v248
	v_and_b32_e32 v143, 0xffff0000, v248
	v_lshlrev_b32_e32 v144, 16, v249
	v_and_b32_e32 v145, 0xffff0000, v249
	v_lshlrev_b32_e32 v146, 16, v184
	v_and_b32_e32 v147, 0xffff0000, v184
	v_lshlrev_b32_e32 v148, 16, v185
	v_and_b32_e32 v149, 0xffff0000, v185
	v_pk_fma_f32 v[10:11], v[10:11], v[144:145], v[148:149]
	v_pk_fma_f32 v[8:9], v[8:9], v[142:143], v[146:147]
	v_cvt_pk_bf16_f32 v184, v8, v9
	v_cvt_pk_bf16_f32 v185, v10, v11
	v_lshlrev_b32_e32 v142, 16, v250
	v_and_b32_e32 v143, 0xffff0000, v250
	v_lshlrev_b32_e32 v144, 16, v251
	v_and_b32_e32 v145, 0xffff0000, v251
	v_lshlrev_b32_e32 v146, 16, v150
	v_and_b32_e32 v147, 0xffff0000, v150
	v_lshlrev_b32_e32 v148, 16, v151
	v_and_b32_e32 v149, 0xffff0000, v151
	v_pk_fma_f32 v[6:7], v[6:7], v[144:145], v[148:149]
	v_pk_fma_f32 v[4:5], v[4:5], v[142:143], v[146:147]
	v_cvt_pk_bf16_f32 v150, v4, v5
	v_cvt_pk_bf16_f32 v151, v6, v7
	v_lshlrev_b32_e32 v142, 16, v252
	v_and_b32_e32 v143, 0xffff0000, v252
	v_lshlrev_b32_e32 v144, 16, v253
	v_and_b32_e32 v145, 0xffff0000, v253
	v_lshlrev_b32_e32 v146, 16, v152
	v_and_b32_e32 v147, 0xffff0000, v152
	v_lshlrev_b32_e32 v148, 16, v153
	v_and_b32_e32 v149, 0xffff0000, v153
	v_pk_fma_f32 v[2:3], v[2:3], v[144:145], v[148:149]
	v_pk_fma_f32 v[0:1], v[0:1], v[142:143], v[146:147]
	v_cvt_pk_bf16_f32 v152, v0, v1
	v_cvt_pk_bf16_f32 v153, v2, v3
	global_store_dwordx4 v193, v[182:185], s[88:89]
	global_store_dwordx4 v193, v[150:153], s[88:89] offset:256
	s_branch .Lem_done
; __device__ __forceinline__ f32x4 ld_bf4(const bf16_t* p) { const u32x2 w = *(const u32x2*)p; f32x4 r; r[0] = __uint_as_float(w.x << 16); r[1] = __uint_as_float(w.x & 0xffff0000u); r[2] = __uint_as_float(w.y << 16); r[3] = __uint_as_float(w.y & 0xffff0000u); return r; }
; __device__ __forceinline__ void st_bf4(bf16_t* p, const f32x4 v) { u32x2 w; w.x = cvt_pk_bf16(v[0], v[1]); w.y = cvt_pk_bf16(v[2], v[3]); *(u32x2*)p = w; }
;     __device__ __forceinline__ void operator()(const f32x4 (&acc)[2][2][4][2], const Unit& u, int wr, int wc, int fr, int fq) const {
;     ...
;         for (int ai = 0; ai < 2; ++ai)
; #pragma unroll
;             for (int m = 0; m < 4; ++m) { const int row = pm * 256 + ai * 128 + wr * 64 + m * 16 + fr;
; #pragma unroll
;                 for (int bj = 0; bj < 2; ++bj)
; #pragma unroll
;                     for (int n = 0; n < 2; ++n) { const int col = pn * 256 + bj * 128 + wc * 32 + 8 * fq + 4 * n; const f32x4 v = acc[ai][bj][m][n];
;                         const f32x4 g = ld_bf4(GT + (size_t)row * 3072 + br * 1024 + col);
;                         bf16_t* mp = M16 + (size_t)row * 1024 + col;
;                         if (br == 0) st_bf4(mp, g * v); else st_bf4(mp, ld_bf4(mp) + g * v); } }
.Lem_first:
	global_load_dwordx4 v[198:201], v170, s[2:3]
	global_load_dwordx4 v[202:205], v170, s[2:3] offset:256
	global_load_dwordx4 v[206:209], v171, s[2:3]
	global_load_dwordx4 v[210:213], v171, s[2:3] offset:256
	global_load_dwordx4 v[214:217], v172, s[2:3]
	global_load_dwordx4 v[218:221], v172, s[2:3] offset:256
	global_load_dwordx4 v[222:225], v173, s[2:3]
	global_load_dwordx4 v[226:229], v173, s[2:3] offset:256
	global_load_dwordx4 v[230:233], v174, s[2:3]
	global_load_dwordx4 v[234:237], v174, s[2:3] offset:256
	global_load_dwordx4 v[238:241], v175, s[2:3]
	global_load_dwordx4 v[242:245], v175, s[2:3] offset:256
	global_load_dwordx4 v[246:249], v176, s[2:3]
	global_load_dwordx4 v[250:253], v176, s[2:3] offset:256
	global_load_dwordx4 v[182:185], v177, s[2:3]
	global_load_dwordx4 v[150:153], v177, s[2:3] offset:256
	s_waitcnt vmcnt(14)
	v_lshlrev_b32_e32 v142, 16, v198
	v_and_b32_e32 v143, 0xffff0000, v198
	v_lshlrev_b32_e32 v144, 16, v199
	v_and_b32_e32 v145, 0xffff0000, v199
	v_pk_mul_f32 v[128:129], v[128:129], v[144:145]
	v_pk_mul_f32 v[126:127], v[126:127], v[142:143]
	v_cvt_pk_bf16_f32 v198, v126, v127
	v_cvt_pk_bf16_f32 v199, v128, v129
	v_lshlrev_b32_e32 v142, 16, v200
	v_and_b32_e32 v143, 0xffff0000, v200
	v_lshlrev_b32_e32 v144, 16, v201
	v_and_b32_e32 v145, 0xffff0000, v201
	v_pk_mul_f32 v[124:125], v[124:125], v[144:145]
	v_pk_mul_f32 v[122:123], v[122:123], v[142:143]
	v_cvt_pk_bf16_f32 v200, v122, v123
	v_cvt_pk_bf16_f32 v201, v124, v125
	v_lshlrev_b32_e32 v142, 16, v202
	v_and_b32_e32 v143, 0xffff0000, v202
	v_lshlrev_b32_e32 v144, 16, v203
	v_and_b32_e32 v145, 0xffff0000, v203
	v_pk_mul_f32 v[120:121], v[120:121], v[144:145]
	v_pk_mul_f32 v[118:119], v[118:119], v[142:143]
	v_cvt_pk_bf16_f32 v202, v118, v119
	v_cvt_pk_bf16_f32 v203, v120, v121
	v_lshlrev_b32_e32 v142, 16, v204
	v_and_b32_e32 v143, 0xffff0000, v204
	v_lshlrev_b32_e32 v144, 16, v205
	v_and_b32_e32 v145, 0xffff0000, v205
	v_pk_mul_f32 v[116:117], v[116:117], v[144:145]
	v_pk_mul_f32 v[114:115], v[114:115], v[142:143]
	v_cvt_pk_bf16_f32 v204, v114, v115
	v_cvt_pk_bf16_f32 v205, v116, v117
	global_store_dwordx4 v186, v[198:201], s[88:89]
	global_store_dwordx4 v186, v[202:205], s[88:89] offset:256
	s_waitcnt vmcnt(14)
	v_lshlrev_b32_e32 v142, 16, v206
	v_and_b32_e32 v143, 0xffff0000, v206
	v_lshlrev_b32_e32 v144, 16, v207
	v_and_b32_e32 v145, 0xffff0000, v207
	v_pk_mul_f32 v[112:113], v[112:113], v[144:145]
	v_pk_mul_f32 v[110:111], v[110:111], v[142:143]
	v_cvt_pk_bf16_f32 v206, v110, v111
	v_cvt_pk_bf16_f32 v207, v112, v113
	v_lshlrev_b32_e32 v142, 16, v208
	v_and_b32_e32 v143, 0xffff0000, v208
	v_lshlrev_b32_e32 v144, 16, v209
	v_and_b32_e32 v145, 0xffff0000, v209
	v_pk_mul_f32 v[108:109], v[108:109], v[144:145]
	v_pk_mul_f32 v[106:107], v[106:107], v[142:143]
	v_cvt_pk_bf16_f32 v208, v106, v107
	v_cvt_pk_bf16_f32 v209, v108, v109
	v_lshlrev_b32_e32 v142, 16, v210
	v_and_b32_e32 v143, 0xffff0000, v210
	v_lshlrev_b32_e32 v144, 16, v211
	v_and_b32_e32 v145, 0xffff0000, v211
	v_pk_mul_f32 v[104:105], v[104:105], v[144:145]
	v_pk_mul_f32 v[102:103], v[102:103], v[142:143]
	v_cvt_pk_bf16_f32 v210, v102, v103
	v_cvt_pk_bf16_f32 v211, v104, v105
	v_lshlrev_b32_e32 v142, 16, v212
	v_and_b32_e32 v143, 0xffff0000, v212
	v_lshlrev_b32_e32 v144, 16, v213
	v_and_b32_e32 v145, 0xffff0000, v213
	v_pk_mul_f32 v[100:101], v[100:101], v[144:145]
	v_pk_mul_f32 v[98:99], v[98:99], v[142:143]
	v_cvt_pk_bf16_f32 v212, v98, v99
	v_cvt_pk_bf16_f32 v213, v100, v101
	global_store_dwordx4 v187, v[206:209], s[88:89]
	global_store_dwordx4 v187, v[210:213], s[88:89] offset:256
	s_waitcnt vmcnt(14)
	v_lshlrev_b32_e32 v142, 16, v214
	v_and_b32_e32 v143, 0xffff0000, v214
	v_lshlrev_b32_e32 v144, 16, v215
	v_and_b32_e32 v145, 0xffff0000, v215
	v_pk_mul_f32 v[94:95], v[94:95], v[144:145]
	v_pk_mul_f32 v[92:93], v[92:93], v[142:143]
	v_cvt_pk_bf16_f32 v214, v92, v93
	v_cvt_pk_bf16_f32 v215, v94, v95
	v_lshlrev_b32_e32 v142, 16, v216
	v_and_b32_e32 v143, 0xffff0000, v216
	v_lshlrev_b32_e32 v144, 16, v217
	v_and_b32_e32 v145, 0xffff0000, v217
	v_pk_mul_f32 v[90:91], v[90:91], v[144:145]
	v_pk_mul_f32 v[88:89], v[88:89], v[142:143]
	v_cvt_pk_bf16_f32 v216, v88, v89
	v_cvt_pk_bf16_f32 v217, v90, v91
	v_lshlrev_b32_e32 v142, 16, v218
	v_and_b32_e32 v143, 0xffff0000, v218
	v_lshlrev_b32_e32 v144, 16, v219
	v_and_b32_e32 v145, 0xffff0000, v219
	v_pk_mul_f32 v[86:87], v[86:87], v[144:145]
	v_pk_mul_f32 v[84:85], v[84:85], v[142:143]
	v_cvt_pk_bf16_f32 v218, v84, v85
	v_cvt_pk_bf16_f32 v219, v86, v87
	v_lshlrev_b32_e32 v142, 16, v220
	v_and_b32_e32 v143, 0xffff0000, v220
	v_lshlrev_b32_e32 v144, 16, v221
	v_and_b32_e32 v145, 0xffff0000, v221
	v_pk_mul_f32 v[82:83], v[82:83], v[144:145]
	v_pk_mul_f32 v[80:81], v[80:81], v[142:143]
	v_cvt_pk_bf16_f32 v220, v80, v81
	v_cvt_pk_bf16_f32 v221, v82, v83
	global_store_dwordx4 v188, v[214:217], s[88:89]
	global_store_dwordx4 v188, v[218:221], s[88:89] offset:256
	s_waitcnt vmcnt(14)
	v_lshlrev_b32_e32 v142, 16, v222
	v_and_b32_e32 v143, 0xffff0000, v222
	v_lshlrev_b32_e32 v144, 16, v223
	v_and_b32_e32 v145, 0xffff0000, v223
	v_pk_mul_f32 v[78:79], v[78:79], v[144:145]
	v_pk_mul_f32 v[76:77], v[76:77], v[142:143]
	v_cvt_pk_bf16_f32 v222, v76, v77
	v_cvt_pk_bf16_f32 v223, v78, v79
	v_lshlrev_b32_e32 v142, 16, v224
	v_and_b32_e32 v143, 0xffff0000, v224
	v_lshlrev_b32_e32 v144, 16, v225
	v_and_b32_e32 v145, 0xffff0000, v225
	v_pk_mul_f32 v[74:75], v[74:75], v[144:145]
	v_pk_mul_f32 v[72:73], v[72:73], v[142:143]
	v_cvt_pk_bf16_f32 v224, v72, v73
	v_cvt_pk_bf16_f32 v225, v74, v75
	v_lshlrev_b32_e32 v142, 16, v226
	v_and_b32_e32 v143, 0xffff0000, v226
	v_lshlrev_b32_e32 v144, 16, v227
	v_and_b32_e32 v145, 0xffff0000, v227
	v_pk_mul_f32 v[70:71], v[70:71], v[144:145]
	v_pk_mul_f32 v[68:69], v[68:69], v[142:143]
	v_cvt_pk_bf16_f32 v226, v68, v69
	v_cvt_pk_bf16_f32 v227, v70, v71
	v_lshlrev_b32_e32 v142, 16, v228
	v_and_b32_e32 v143, 0xffff0000, v228
	v_lshlrev_b32_e32 v144, 16, v229
	v_and_b32_e32 v145, 0xffff0000, v229
	v_pk_mul_f32 v[66:67], v[66:67], v[144:145]
	v_pk_mul_f32 v[64:65], v[64:65], v[142:143]
	v_cvt_pk_bf16_f32 v228, v64, v65
	v_cvt_pk_bf16_f32 v229, v66, v67
	global_store_dwordx4 v189, v[222:225], s[88:89]
	global_store_dwordx4 v189, v[226:229], s[88:89] offset:256
	s_waitcnt vmcnt(14)
; __device__ __forceinline__ f32x4 ld_bf4(const bf16_t* p) { const u32x2 w = *(const u32x2*)p; f32x4 r; r[0] = __uint_as_float(w.x << 16); r[1] = __uint_as_float(w.x & 0xffff0000u); r[2] = __uint_as_float(w.y << 16); r[3] = __uint_as_float(w.y & 0xffff0000u); return r; }
; __device__ __forceinline__ void st_bf4(bf16_t* p, const f32x4 v) { u32x2 w; w.x = cvt_pk_bf16(v[0], v[1]); w.y = cvt_pk_bf16(v[2], v[3]); *(u32x2*)p = w; }
;     __device__ __forceinline__ void operator()(const f32x4 (&acc)[2][2][4][2], const Unit& u, int wr, int wc, int fr, int fq) const {
;     ...
;         for (int ai = 0; ai < 2; ++ai)
; #pragma unroll
;             for (int m = 0; m < 4; ++m) { const int row = pm * 256 + ai * 128 + wr * 64 + m * 16 + fr;
; #pragma unroll
;                 for (int bj = 0; bj < 2; ++bj)
; #pragma unroll
;                     for (int n = 0; n < 2; ++n) { const int col = pn * 256 + bj * 128 + wc * 32 + 8 * fq + 4 * n; const f32x4 v = acc[ai][bj][m][n];
;                         const f32x4 g = ld_bf4(GT + (size_t)row * 3072 + br * 1024 + col);
;                         bf16_t* mp = M16 + (size_t)row * 1024 + col;
;                         if (br == 0) st_bf4(mp, g * v); else st_bf4(mp, ld_bf4(mp) + g * v); } }
	v_lshlrev_b32_e32 v142, 16, v230
	v_and_b32_e32 v143, 0xffff0000, v230
	v_lshlrev_b32_e32 v144, 16, v231
	v_and_b32_e32 v145, 0xffff0000, v231
	v_pk_mul_f32 v[62:63], v[62:63], v[144:145]
	v_pk_mul_f32 v[60:61], v[60:61], v[142:143]
	v_cvt_pk_bf16_f32 v230, v60, v61
	v_cvt_pk_bf16_f32 v231, v62, v63
	v_lshlrev_b32_e32 v142, 16, v232
	v_and_b32_e32 v143, 0xffff0000, v232
	v_lshlrev_b32_e32 v144, 16, v233
	v_and_b32_e32 v145, 0xffff0000, v233
	v_pk_mul_f32 v[58:59], v[58:59], v[144:145]
	v_pk_mul_f32 v[56:57], v[56:57], v[142:143]
	v_cvt_pk_bf16_f32 v232, v56, v57
	v_cvt_pk_bf16_f32 v233, v58, v59
	v_lshlrev_b32_e32 v142, 16, v234
	v_and_b32_e32 v143, 0xffff0000, v234
	v_lshlrev_b32_e32 v144, 16, v235
	v_and_b32_e32 v145, 0xffff0000, v235
	v_pk_mul_f32 v[54:55], v[54:55], v[144:145]
	v_pk_mul_f32 v[52:53], v[52:53], v[142:143]
	v_cvt_pk_bf16_f32 v234, v52, v53
	v_cvt_pk_bf16_f32 v235, v54, v55
	v_lshlrev_b32_e32 v142, 16, v236
	v_and_b32_e32 v143, 0xffff0000, v236
	v_lshlrev_b32_e32 v144, 16, v237
	v_and_b32_e32 v145, 0xffff0000, v237
	v_pk_mul_f32 v[50:51], v[50:51], v[144:145]
	v_pk_mul_f32 v[48:49], v[48:49], v[142:143]
	v_cvt_pk_bf16_f32 v236, v48, v49
	v_cvt_pk_bf16_f32 v237, v50, v51
	global_store_dwordx4 v190, v[230:233], s[88:89]
	global_store_dwordx4 v190, v[234:237], s[88:89] offset:256
	s_waitcnt vmcnt(14)
	v_lshlrev_b32_e32 v142, 16, v238
	v_and_b32_e32 v143, 0xffff0000, v238
	v_lshlrev_b32_e32 v144, 16, v239
	v_and_b32_e32 v145, 0xffff0000, v239
	v_pk_mul_f32 v[46:47], v[46:47], v[144:145]
	v_pk_mul_f32 v[44:45], v[44:45], v[142:143]
	v_cvt_pk_bf16_f32 v238, v44, v45
	v_cvt_pk_bf16_f32 v239, v46, v47
	v_lshlrev_b32_e32 v142, 16, v240
	v_and_b32_e32 v143, 0xffff0000, v240
	v_lshlrev_b32_e32 v144, 16, v241
	v_and_b32_e32 v145, 0xffff0000, v241
	v_pk_mul_f32 v[42:43], v[42:43], v[144:145]
	v_pk_mul_f32 v[40:41], v[40:41], v[142:143]
	v_cvt_pk_bf16_f32 v240, v40, v41
	v_cvt_pk_bf16_f32 v241, v42, v43
	v_lshlrev_b32_e32 v142, 16, v242
	v_and_b32_e32 v143, 0xffff0000, v242
	v_lshlrev_b32_e32 v144, 16, v243
	v_and_b32_e32 v145, 0xffff0000, v243
	v_pk_mul_f32 v[38:39], v[38:39], v[144:145]
	v_pk_mul_f32 v[36:37], v[36:37], v[142:143]
	v_cvt_pk_bf16_f32 v242, v36, v37
	v_cvt_pk_bf16_f32 v243, v38, v39
	v_lshlrev_b32_e32 v142, 16, v244
	v_and_b32_e32 v143, 0xffff0000, v244
	v_lshlrev_b32_e32 v144, 16, v245
	v_and_b32_e32 v145, 0xffff0000, v245
	v_pk_mul_f32 v[34:35], v[34:35], v[144:145]
	v_pk_mul_f32 v[32:33], v[32:33], v[142:143]
	v_cvt_pk_bf16_f32 v244, v32, v33
	v_cvt_pk_bf16_f32 v245, v34, v35
	global_store_dwordx4 v191, v[238:241], s[88:89]
	global_store_dwordx4 v191, v[242:245], s[88:89] offset:256
	s_waitcnt vmcnt(14)
	v_lshlrev_b32_e32 v142, 16, v246
	v_and_b32_e32 v143, 0xffff0000, v246
	v_lshlrev_b32_e32 v144, 16, v247
	v_and_b32_e32 v145, 0xffff0000, v247
	v_pk_mul_f32 v[30:31], v[30:31], v[144:145]
	v_pk_mul_f32 v[28:29], v[28:29], v[142:143]
	v_cvt_pk_bf16_f32 v246, v28, v29
	v_cvt_pk_bf16_f32 v247, v30, v31
	v_lshlrev_b32_e32 v142, 16, v248
	v_and_b32_e32 v143, 0xffff0000, v248
	v_lshlrev_b32_e32 v144, 16, v249
	v_and_b32_e32 v145, 0xffff0000, v249
	v_pk_mul_f32 v[26:27], v[26:27], v[144:145]
	v_pk_mul_f32 v[24:25], v[24:25], v[142:143]
	v_cvt_pk_bf16_f32 v248, v24, v25
	v_cvt_pk_bf16_f32 v249, v26, v27
	v_lshlrev_b32_e32 v142, 16, v250
	v_and_b32_e32 v143, 0xffff0000, v250
	v_lshlrev_b32_e32 v144, 16, v251
	v_and_b32_e32 v145, 0xffff0000, v251
	v_pk_mul_f32 v[22:23], v[22:23], v[144:145]
	v_pk_mul_f32 v[20:21], v[20:21], v[142:143]
	v_cvt_pk_bf16_f32 v250, v20, v21
	v_cvt_pk_bf16_f32 v251, v22, v23
	v_lshlrev_b32_e32 v142, 16, v252
	v_and_b32_e32 v143, 0xffff0000, v252
	v_lshlrev_b32_e32 v144, 16, v253
	v_and_b32_e32 v145, 0xffff0000, v253
	v_pk_mul_f32 v[18:19], v[18:19], v[144:145]
	v_pk_mul_f32 v[16:17], v[16:17], v[142:143]
	v_cvt_pk_bf16_f32 v252, v16, v17
	v_cvt_pk_bf16_f32 v253, v18, v19
	global_store_dwordx4 v192, v[246:249], s[88:89]
	global_store_dwordx4 v192, v[250:253], s[88:89] offset:256
	s_waitcnt vmcnt(14)
	v_lshlrev_b32_e32 v142, 16, v182
	v_and_b32_e32 v143, 0xffff0000, v182
	v_lshlrev_b32_e32 v144, 16, v183
	v_and_b32_e32 v145, 0xffff0000, v183
	v_pk_mul_f32 v[14:15], v[14:15], v[144:145]
	v_pk_mul_f32 v[12:13], v[12:13], v[142:143]
	v_cvt_pk_bf16_f32 v182, v12, v13
	v_cvt_pk_bf16_f32 v183, v14, v15
	v_lshlrev_b32_e32 v142, 16, v184
	v_and_b32_e32 v143, 0xffff0000, v184
	v_lshlrev_b32_e32 v144, 16, v185
	v_and_b32_e32 v145, 0xffff0000, v185
	v_pk_mul_f32 v[10:11], v[10:11], v[144:145]
	v_pk_mul_f32 v[8:9], v[8:9], v[142:143]
	v_cvt_pk_bf16_f32 v184, v8, v9
	v_cvt_pk_bf16_f32 v185, v10, v11
	v_lshlrev_b32_e32 v142, 16, v150
	v_and_b32_e32 v143, 0xffff0000, v150
	v_lshlrev_b32_e32 v144, 16, v151
	v_and_b32_e32 v145, 0xffff0000, v151
	v_pk_mul_f32 v[6:7], v[6:7], v[144:145]
	v_pk_mul_f32 v[4:5], v[4:5], v[142:143]
	v_cvt_pk_bf16_f32 v150, v4, v5
	v_cvt_pk_bf16_f32 v151, v6, v7
	v_lshlrev_b32_e32 v142, 16, v152
	v_and_b32_e32 v143, 0xffff0000, v152
	v_lshlrev_b32_e32 v144, 16, v153
	v_and_b32_e32 v145, 0xffff0000, v153
	v_pk_mul_f32 v[2:3], v[2:3], v[144:145]
	v_pk_mul_f32 v[0:1], v[0:1], v[142:143]
	v_cvt_pk_bf16_f32 v152, v0, v1
	v_cvt_pk_bf16_f32 v153, v2, v3
	global_store_dwordx4 v193, v[182:185], s[88:89]
	global_store_dwordx4 v193, v[150:153], s[88:89] offset:256
.Lem_done:
	s_andn2_b64 vcc, exec, s[16:17]
	s_mov_b64 s[6:7], -1
	s_cbranch_vccnz .LBB0_289

; #define LAS __attribute__((address_space(3)))
; DI void s5_load_consts(S5C& K, const unsigned char* ws, int lg, int lane) {
;     const bf16_t* BBF = (const bf16_t*)(ws + WS_TAB + TB_BBF); const bf16_t* CF = (const bf16_t*)(ws + WS_TAB + TB_CF); const float* AB = (const float*)(ws + WS_TAB + TB_ABAR);
; #pragma unroll
;     for (int t = 0; t < 4; ++t) { K.bbf[t] = *(const bf16x8*)(BBF + (((size_t)lg * 4 + t) * 64 + lane) * 8); K.cf[t] = *(const bf16x8*)(CF + (((size_t)lg * 4 + t) * 64 + lane) * 8); }
; #pragma unroll
;     for (int st = 0; st < 2; ++st) { const int p = st * 32 + (lane & 31); K.are[st] = AB[((size_t)lg * 64 + p) * 2]; K.aim[st] = AB[((size_t)lg * 64 + p) * 2 + 1]; }
; }
; DI void s5_prompt_task(LAS unsigned char* lds, int task, int l, ArgsP a, const float* U, bf16_t* YC0, int tid) {
;     const int b = task >> 5, g = task & 31, lg = l * 32 + g, wave = tid >> 6, lane = tid & 63;
;     LAS bf16_t* Hs = (LAS bf16_t*)(lds + wave * 8704);
;     LAS float* Es = (LAS float*)(lds + 8 * 8704);
;     S5C K; s5_load_consts(K, a->ws, lg, lane);
;     const float* dvec = a->in[24] + l * 512 + g * 16;
;     const int rowb = b * 2048 + wave * 256;
;     float hre[2] = {0.f, 0.f}, him[2] = {0.f, 0.f};
;     for (int tl = 0; tl < 8; ++tl) s5_tile<false>(K, U, rowb + tl * 32, g, 8, 32, hre, him, Hs, dvec, YC0, lane);
.LBB0_900:
	s_and_b32 s42, s39, 31
	s_or_b32 s14, s42, s33
	s_ashr_i32 s15, s14, 31
	s_lshl_b64 s[30:31], s[14:15], 12
	v_lshl_or_b32 v0, v170, 1, s30
	v_mov_b32_e32 v1, s31
	v_lshl_add_u64 v[2:3], s[18:19], 0, v[0:1]
	s_ashr_i32 s43, s39, 5
	v_lshl_add_u64 v[4:5], s[20:21], 0, v[0:1]
	global_load_dwordx4 v[98:101], v[2:3], off
	global_load_dwordx4 v[102:105], v[4:5], off
	v_mov_b32_e32 v3, s31
	s_lshl_b64 s[30:31], s[14:15], 9
	v_or_b32_e32 v2, 0x400, v0
	s_add_u32 s14, s22, s30
	v_lshl_add_u64 v[4:5], s[18:19], 0, v[2:3]
	s_addc_u32 s15, s23, s31
	v_lshlrev_b32_e32 v6, 2, v171
	v_lshl_add_u64 v[2:3], s[20:21], 0, v[2:3]
	global_load_dwordx2 v[144:145], v6, s[14:15]
	global_load_dwordx2 v[150:151], v134, s[14:15]
	global_load_dwordx4 v[106:109], v[4:5], off
	global_load_dwordx4 v[110:113], v[2:3], off
	v_or_b32_e32 v2, 0x800, v0
	v_mov_b32_e32 v3, v1
	v_lshl_add_u64 v[4:5], s[18:19], 0, v[2:3]
	v_lshl_add_u64 v[2:3], s[20:21], 0, v[2:3]
	v_or_b32_e32 v0, 0xc00, v0
	global_load_dwordx4 v[114:117], v[4:5], off
	global_load_dwordx4 v[118:121], v[2:3], off
	v_lshl_add_u64 v[2:3], s[18:19], 0, v[0:1]
	v_lshl_add_u64 v[0:1], s[20:21], 0, v[0:1]
	global_load_dwordx4 v[122:125], v[2:3], off
	global_load_dwordx4 v[126:129], v[0:1], off
	s_lshl_b32 s45, s42, 4
	s_lshl_b32 s44, s43, 11
	s_lshl_b32 s14, s42, 6
	s_add_u32 s14, s4, s14
	v_mov_b32_e32 v143, v97
	v_mov_b32_e32 v96, v97
	v_add_u32_e32 v0, s44, v135
	s_addc_u32 s15, s5, 0
	s_mov_b32 s52, 0
	v_mov_b64_e32 v[78:79], v[96:97]
	v_or_b32_e32 v179, v0, v132
	v_lshl_add_u64 v[64:65], s[14:15], 0, v[142:143]
	v_mov_b64_e32 v[80:81], v[96:97]
	s_waitcnt vmcnt(0)
	v_pk_mov_b32 v[152:153], v[144:145], v[144:145] op_sel:[1,0]
	v_pk_mov_b32 v[154:155], v[150:151], v[150:151] op_sel:[1,0]
	v_mov_b32_e32 v66, v144
	v_mov_b32_e32 v67, v151
	v_mov_b32_e32 v68, v144
	v_mov_b32_e32 v69, v150
	v_mov_b32_e32 v70, v145
	v_mov_b32_e32 v71, v151
	v_pk_mov_b32 v[72:73], v[144:145], v[150:151] op_sel:[1,0]
	v_mov_b32_e32 v74, v151
	v_mov_b32_e32 v75, v145
	v_mov_b32_e32 v76, v150
	v_mov_b32_e32 v77, v144
	v_mov_b32_e32 v156, v145
	v_add_u32_e32 v0, s52, v179
	v_ashrrev_i32_e32 v1, 31, v0
	v_lshlrev_b64 v[0:1], 11, v[0:1]
	v_lshl_add_u64 v[4:5], v[64:65], 0, v[0:1]
	global_load_dwordx4 v[198:201], v[4:5], off
	global_load_dwordx4 v[202:205], v[4:5], off offset:16
	s_branch .LBB0_902

; DI bf16x8 pack8(const f32x4 a, const f32x4 b) { u32x4 p; p.x = cvt_pk_bf16(a[0], a[1]); p.y = cvt_pk_bf16(a[2], a[3]); p.z = cvt_pk_bf16(b[0], b[1]); p.w = cvt_pk_bf16(b[2], b[3]); return __builtin_bit_cast(bf16x8, p); }
; #define MFMA32(a, b, c) __builtin_amdgcn_mfma_f32_32x32x16_bf16((a), (b), (c), 0, 0, 0)
; template <bool OUT>
; DI void s5_tile(const S5C& K, const float* U, int row0, int g, int nruns, int nvalid, float (&hre)[2], float (&him)[2], LAS bf16_t* Hs, const float* dvec, bf16_t* YC0, int lane) {
;     ...
;     if (tok < nvalid) { const float* up = U + (size_t)(row0 + tok) * 512 + g * 16 + half * 8; af = pack8(*(const f32x4*)up, *(const f32x4*)(up + 4)); }
;     f32x16 z16;
; #pragma unroll
;     for (int i = 0; i < 16; ++i) z16[i] = 0.f;
;     f32x16 dre[2], dim[2];
; #pragma unroll
;     for (int st = 0; st < 2; ++st) { dre[st] = MFMA32(af, K.bbf[st], z16); dim[st] = MFMA32(af, K.bbf[2 + st], z16); }
; #pragma unroll
;     for (int r = 0; r < 8; ++r) {
;         if (r < nruns) {
;             const int hf = r & 1, i0 = 4 * (r >> 1);
;             if (half == hf) {
; #pragma unroll
;                 for (int k = 0; k < 4; ++k)
; #pragma unroll
;                     for (int st = 0; st < 2; ++st) { const float nr = K.are[st] * hre[st] - K.aim[st] * him[st] + dre[st][i0 + k]; const float ni = K.are[st] * him[st] + K.aim[st] * hre[st] + dim[st][i0 + k];
;                         hre[st] = nr; him[st] = ni; dre[st][i0 + k] = nr; dim[st][i0 + k] = ni; }
;             }
; #pragma unroll
;             for (int st = 0; st < 2; ++st) { const float pr = __shfl_xor(hre[st], 32), pi = __shfl_xor(him[st], 32); if (half != hf) { hre[st] = pr; him[st] = pi; } }
;         }
.LBB0_902:
	s_waitcnt vmcnt(0)
	v_cvt_pk_bf16_f32 v48, v198, v199
	v_cvt_pk_bf16_f32 v49, v200, v201
	v_cvt_pk_bf16_f32 v50, v202, v203
	v_cvt_pk_bf16_f32 v51, v204, v205
	v_add_u32_e32 v0, s52, v179
	v_add_u32_e32 v0, 32, v0
	v_ashrrev_i32_e32 v1, 31, v0
	v_lshlrev_b64 v[0:1], 11, v[0:1]
	v_lshl_add_u64 v[4:5], v[64:65], 0, v[0:1]
	global_load_dwordx4 v[198:201], v[4:5], off
	global_load_dwordx4 v[202:205], v[4:5], off offset:16
	v_mfma_f32_32x32x16_bf16 v[0:15], v[48:51], v[98:101], 0
	v_mfma_f32_32x32x16_bf16 v[32:47], v[48:51], v[114:117], 0
	v_mfma_f32_32x32x16_bf16 v[16:31], v[48:51], v[106:109], 0
	v_mfma_f32_32x32x16_bf16 v[48:63], v[48:51], v[122:125], 0
	s_and_saveexec_b64 s[40:41], s[6:7]
	s_cbranch_execz .LBB0_904
	v_pk_mul_f32 v[82:83], v[152:153], v[80:81] op_sel_hi:[1,0]
	s_nop 0
	v_pk_fma_f32 v[84:85], v[144:145], v[78:79], v[82:83] neg_lo:[0,0,1] neg_hi:[0,0,1]
	v_pk_fma_f32 v[82:83], v[144:145], v[78:79], v[82:83] op_sel_hi:[1,0,1]
	s_nop 0
	v_mov_b32_e32 v85, v83
	s_nop 0
	v_mov_b32_e32 v82, v0
	v_mov_b32_e32 v83, v32
	v_pk_add_f32 v[82:83], v[84:85], v[82:83]
	s_nop 0
	v_pk_mul_f32 v[84:85], v[144:145], v[82:83]
	s_nop 0
	v_sub_f32_e32 v0, v84, v85
	v_add_f32_e32 v84, v1, v0
	v_pk_mul_f32 v[0:1], v[152:153], v[82:83]
	s_nop 0
	v_add_f32_e32 v0, v0, v1
	v_add_f32_e32 v0, v33, v0
	v_pk_mul_f32 v[32:33], v[154:155], v[80:81] op_sel:[0,1]
	s_nop 0
	v_pk_fma_f32 v[80:81], v[150:151], v[78:79], v[32:33] op_sel:[0,1,0] neg_lo:[0,0,1] neg_hi:[0,0,1]
	v_pk_fma_f32 v[32:33], v[150:151], v[78:79], v[32:33] op_sel:[0,1,0]
	s_nop 0
	v_mov_b32_e32 v81, v33
	v_mov_b32_e32 v32, v16
	v_mov_b32_e32 v33, v48
	v_pk_add_f32 v[86:87], v[80:81], v[32:33]
	s_nop 0
	v_pk_mul_f32 v[32:33], v[150:151], v[86:87]
	s_nop 0
	v_sub_f32_e32 v1, v32, v33
	v_add_f32_e32 v88, v17, v1
	v_pk_mul_f32 v[16:17], v[154:155], v[86:87]
	s_nop 0
	v_add_f32_e32 v1, v16, v17
	v_add_f32_e32 v16, v49, v1
	v_pk_mul_f32 v[32:33], v[144:145], v[0:1] op_sel_hi:[1,0]
	v_pk_mul_f32 v[78:79], v[150:151], v[16:17] op_sel_hi:[1,0]
	v_pk_fma_f32 v[48:49], v[152:153], v[84:85], v[32:33] op_sel_hi:[1,0,1] neg_lo:[0,0,1] neg_hi:[0,0,1]
	v_pk_fma_f32 v[32:33], v[152:153], v[84:85], v[32:33] op_sel_hi:[1,0,1]
	v_pk_fma_f32 v[92:93], v[154:155], v[88:89], v[78:79] op_sel_hi:[1,0,1] neg_lo:[0,0,1] neg_hi:[0,0,1]
	v_pk_fma_f32 v[78:79], v[154:155], v[88:89], v[78:79] op_sel_hi:[1,0,1]
	v_mov_b32_e32 v33, v49
	v_mov_b32_e32 v48, v34
	v_mov_b32_e32 v49, v2
	v_mov_b32_e32 v79, v93
	v_mov_b32_e32 v92, v50
	v_mov_b32_e32 v93, v18
	v_pk_add_f32 v[90:91], v[48:49], v[32:33]
	v_pk_add_f32 v[92:93], v[92:93], v[78:79]
	v_pk_mul_f32 v[32:33], v[144:145], v[90:91] op_sel:[0,1] op_sel_hi:[1,0]
	v_pk_mul_f32 v[48:49], v[156:157], v[90:91]
	v_pk_mul_f32 v[78:79], v[150:151], v[92:93] op_sel:[0,1] op_sel_hi:[1,0]
	v_pk_mul_f32 v[80:81], v[144:145], v[90:91]
	v_mov_b32_e32 v33, v78
	v_mov_b32_e32 v49, v79
	v_pk_add_f32 v[32:33], v[32:33], v[48:49] neg_lo:[0,1] neg_hi:[0,1]
	v_mov_b32_e32 v18, v3
	v_pk_mul_f32 v[2:3], v[150:151], v[92:93]
	v_pk_add_f32 v[78:79], v[18:19], v[32:33]
	v_mov_b32_e32 v18, v81
	v_mov_b32_e32 v19, v3
	v_mov_b32_e32 v81, v2
	v_pk_add_f32 v[2:3], v[18:19], v[80:81]
	v_mov_b32_e32 v50, v35
	v_pk_add_f32 v[80:81], v[50:51], v[2:3]
	v_mov_b32_e32 v48, v87
	v_mov_b32_e32 v49, v16
	v_mov_b32_e32 v50, v92
	v_mov_b32_e32 v51, v81
	v_mov_b32_e32 v32, v83
	v_mov_b32_e32 v33, v0
	v_mov_b32_e32 v34, v90
	v_mov_b32_e32 v35, v80
	v_mov_b32_e32 v0, v82
	v_mov_b32_e32 v1, v84
	v_mov_b32_e32 v2, v91
	v_mov_b32_e32 v3, v78
	v_mov_b32_e32 v16, v86
	v_mov_b32_e32 v17, v88
	v_mov_b32_e32 v18, v93
	v_mov_b32_e32 v19, v79

; DI void s5_prompt_task(LAS unsigned char* lds, int task, int l, ArgsP a, const float* U, bf16_t* YC0, int tid) {
;     ...
;     { const float* A256 = (const float*)(a->ws + WS_TAB + TB_ABAR256); float pr[2], pi[2];
; #pragma unroll
;       for (int st = 0; st < 2; ++st) { const int p = st * 32 + (lane & 31); pr[st] = A256[((size_t)lg * 64 + p) * 2]; pi[st] = A256[((size_t)lg * 64 + p) * 2 + 1]; hre[st] = 0.f; him[st] = 0.f; }
;       for (int w = 0; w < wave; ++w) {
; #pragma unroll
;           for (int st = 0; st < 2; ++st) { const float er = Es[(w * 4 + st) * 32 + (lane & 31)], ei = Es[(w * 4 + 2 + st) * 32 + (lane & 31)];
;               const float nr = pr[st] * hre[st] - pi[st] * him[st] + er, ni = pr[st] * him[st] + pi[st] * hre[st] + ei; hre[st] = nr; him[st] = ni; } } }
;     for (int tl = 0; tl < 8; ++tl) s5_tile<true>(K, U, rowb + tl * 32, g, 8, 32, hre, him, Hs, dvec, YC0, lane);
.LBB0_932:
	s_or_b64 exec, exec, s[40:41]
	v_lshlrev_b32_e32 v0, 2, v172
	v_mov_b32_e32 v1, v97
	s_lshl_b32 s56, s45, 2
	v_lshl_add_u64 v[158:159], s[14:15], 0, v[0:1]
	v_or_b32_e32 v96, s45, v175
	v_lshl_add_u64 v[160:161], v[140:141], 0, s[56:57]
	v_add_u32_e32 v180, s44, v177
	s_mov_b32 s30, 0
	v_ashrrev_i32_e32 v1, 31, v179
	v_mov_b32_e32 v0, v179
	v_lshlrev_b64 v[0:1], 11, v[0:1]
	v_lshl_add_u64 v[4:5], v[158:159], 0, v[0:1]
	global_load_dwordx4 v[206:209], v[4:5], off
	global_load_dwordx4 v[210:213], v[4:5], off offset:16
	s_branch .LBB0_934

; DI bf16x8 pack8(const f32x4 a, const f32x4 b) { u32x4 p; p.x = cvt_pk_bf16(a[0], a[1]); p.y = cvt_pk_bf16(a[2], a[3]); p.z = cvt_pk_bf16(b[0], b[1]); p.w = cvt_pk_bf16(b[2], b[3]); return __builtin_bit_cast(bf16x8, p); }
; #define MFMA32(a, b, c) __builtin_amdgcn_mfma_f32_32x32x16_bf16((a), (b), (c), 0, 0, 0)
; template <bool OUT>
; DI void s5_tile(const S5C& K, const float* U, int row0, int g, int nruns, int nvalid, float (&hre)[2], float (&him)[2], LAS bf16_t* Hs, const float* dvec, bf16_t* YC0, int lane) {
;     ...
;     if (tok < nvalid) { const float* up = U + (size_t)(row0 + tok) * 512 + g * 16 + half * 8; af = pack8(*(const f32x4*)up, *(const f32x4*)(up + 4)); }
;     f32x16 z16;
; #pragma unroll
;     for (int i = 0; i < 16; ++i) z16[i] = 0.f;
;     f32x16 dre[2], dim[2];
; #pragma unroll
;     for (int st = 0; st < 2; ++st) { dre[st] = MFMA32(af, K.bbf[st], z16); dim[st] = MFMA32(af, K.bbf[2 + st], z16); }
; #pragma unroll
;     for (int r = 0; r < 8; ++r) {
;         if (r < nruns) {
;             const int hf = r & 1, i0 = 4 * (r >> 1);
;             if (half == hf) {
; #pragma unroll
;                 for (int k = 0; k < 4; ++k)
; #pragma unroll
;                     for (int st = 0; st < 2; ++st) { const float nr = K.are[st] * hre[st] - K.aim[st] * him[st] + dre[st][i0 + k]; const float ni = K.are[st] * him[st] + K.aim[st] * hre[st] + dim[st][i0 + k];
;                         hre[st] = nr; him[st] = ni; dre[st][i0 + k] = nr; dim[st][i0 + k] = ni; }
;             }
; #pragma unroll
;             for (int st = 0; st < 2; ++st) { const float pr = __shfl_xor(hre[st], 32), pi = __shfl_xor(him[st], 32); if (half != hf) { hre[st] = pr; him[st] = pi; } }
;         }
.LBB0_934:
	s_waitcnt vmcnt(0)
	v_cvt_pk_bf16_f32 v0, v206, v207
	v_cvt_pk_bf16_f32 v1, v208, v209
	v_cvt_pk_bf16_f32 v2, v210, v211
	v_cvt_pk_bf16_f32 v3, v212, v213
	v_add_u32_e32 v4, s30, v179
	v_add_u32_e32 v4, 32, v4
	v_ashrrev_i32_e32 v5, 31, v4
	v_lshlrev_b64 v[4:5], 11, v[4:5]
	v_lshl_add_u64 v[4:5], v[158:159], 0, v[4:5]
	global_load_dwordx4 v[206:209], v[4:5], off
	global_load_dwordx4 v[210:213], v[4:5], off offset:16
	v_mfma_f32_32x32x16_bf16 v[32:47], v[0:3], v[98:101], 0
	v_mfma_f32_32x32x16_bf16 v[80:95], v[0:3], v[114:117], 0
	v_mfma_f32_32x32x16_bf16 v[48:63], v[0:3], v[106:109], 0
	v_mfma_f32_32x32x16_bf16 v[64:79], v[0:3], v[122:125], 0
	s_and_saveexec_b64 s[14:15], s[6:7]
	s_cbranch_execz .LBB0_936
	v_pk_mul_f32 v[0:1], v[152:153], v[162:163] op_sel_hi:[1,0]
	v_pk_mul_f32 v[6:7], v[154:155], v[162:163] op_sel:[0,1]
	v_pk_fma_f32 v[2:3], v[144:145], v[164:165], v[0:1] neg_lo:[0,0,1] neg_hi:[0,0,1]
	v_pk_fma_f32 v[0:1], v[144:145], v[164:165], v[0:1] op_sel_hi:[1,0,1]
	v_pk_fma_f32 v[8:9], v[150:151], v[164:165], v[6:7] op_sel:[0,1,0] neg_lo:[0,0,1] neg_hi:[0,0,1]
	v_mov_b32_e32 v3, v1
	s_nop 0
	v_mov_b32_e32 v0, v32
	v_mov_b32_e32 v1, v80
	v_pk_fma_f32 v[6:7], v[150:151], v[164:165], v[6:7] op_sel:[0,1,0]
	v_pk_add_f32 v[0:1], v[2:3], v[0:1]
	v_mov_b32_e32 v9, v7
	v_mov_b32_e32 v6, v48
	v_mov_b32_e32 v7, v64
	v_pk_mul_f32 v[2:3], v[144:145], v[0:1]
	v_pk_mul_f32 v[4:5], v[152:153], v[0:1]
	v_pk_add_f32 v[6:7], v[8:9], v[6:7]
	v_sub_f32_e32 v2, v2, v3
	v_add_f32_e32 v3, v4, v5
	v_pk_mul_f32 v[8:9], v[150:151], v[6:7]
	v_add_f32_e32 v4, v81, v3
	v_sub_f32_e32 v3, v8, v9
	v_pk_mul_f32 v[10:11], v[154:155], v[6:7]
	v_add_f32_e32 v8, v49, v3
	v_add_f32_e32 v3, v10, v11
	v_add_f32_e32 v10, v65, v3
	v_add_f32_e32 v2, v33, v2
	v_pk_mul_f32 v[12:13], v[144:145], v[4:5] op_sel_hi:[1,0]
	v_pk_mul_f32 v[20:21], v[150:151], v[10:11] op_sel_hi:[1,0]
	v_pk_fma_f32 v[14:15], v[152:153], v[2:3], v[12:13] op_sel_hi:[1,0,1] neg_lo:[0,0,1] neg_hi:[0,0,1]
	v_pk_fma_f32 v[12:13], v[152:153], v[2:3], v[12:13] op_sel_hi:[1,0,1]
	v_pk_fma_f32 v[22:23], v[154:155], v[8:9], v[20:21] op_sel_hi:[1,0,1] neg_lo:[0,0,1] neg_hi:[0,0,1]
	v_pk_fma_f32 v[20:21], v[154:155], v[8:9], v[20:21] op_sel_hi:[1,0,1]
	v_mov_b32_e32 v13, v15
	v_mov_b32_e32 v14, v82
	v_mov_b32_e32 v15, v34
	v_mov_b32_e32 v21, v23
	v_mov_b32_e32 v22, v66
	v_mov_b32_e32 v23, v50
	v_pk_add_f32 v[12:13], v[14:15], v[12:13]
	v_pk_add_f32 v[20:21], v[22:23], v[20:21]
	v_pk_mul_f32 v[14:15], v[144:145], v[12:13] op_sel:[0,1] op_sel_hi:[1,0]
	v_pk_mul_f32 v[16:17], v[156:157], v[12:13]
	v_pk_mul_f32 v[22:23], v[150:151], v[20:21] op_sel:[0,1] op_sel_hi:[1,0]
	v_mov_b32_e32 v50, v35
	v_mov_b32_e32 v15, v22
	v_mov_b32_e32 v17, v23
	v_pk_add_f32 v[14:15], v[14:15], v[16:17] neg_lo:[0,1] neg_hi:[0,1]
	v_pk_mul_f32 v[18:19], v[144:145], v[12:13]
	v_pk_add_f32 v[164:165], v[50:51], v[14:15]
	v_pk_mul_f32 v[14:15], v[150:151], v[20:21]
	v_mov_b32_e32 v16, v19
	v_mov_b32_e32 v17, v15
	v_mov_b32_e32 v19, v14
	v_pk_add_f32 v[14:15], v[16:17], v[18:19]
	v_mov_b32_e32 v66, v83
	v_pk_add_f32 v[162:163], v[66:67], v[14:15]
	v_mov_b32_e32 v64, v7
	v_mov_b32_e32 v65, v10
	v_mov_b32_e32 v66, v20
	v_mov_b32_e32 v67, v163
	v_mov_b32_e32 v80, v1
	v_mov_b32_e32 v81, v4
	v_mov_b32_e32 v82, v12
	v_mov_b32_e32 v83, v162
	v_mov_b32_e32 v32, v0
	v_mov_b32_e32 v33, v2
	v_mov_b32_e32 v34, v13
	v_mov_b32_e32 v35, v164
	v_mov_b32_e32 v48, v6
	v_mov_b32_e32 v49, v8
	v_mov_b32_e32 v50, v21
	v_mov_b32_e32 v51, v165

;     __device__ __forceinline__ void operator()(const f32x4 (&acc)[2][2][4][2], const Unit& u, int wr, int wc, int fr, int fq) const {
;         const float* gp = MODG + (size_t)(u.pm >> 3) * cfg::NMOD + u.pn * 256 + wc * 32 + 8 * fq;
;         f32x4 g[2][2];
; #pragma unroll
;         for (int bj = 0; bj < 2; ++bj)
; #pragma unroll
;             for (int n = 0; n < 2; ++n) g[bj][n] = *(const f32x4*)(gp + bj * 128 + n * 4);
; #pragma unroll
;         for (int ai = 0; ai < 2; ++ai)
; #pragma unroll
;             for (int m = 0; m < 4; ++m) { const int row = u.pm * 256 + ai * 128 + wr * 64 + m * 16 + fr;
; #pragma unroll
;                 for (int bj = 0; bj < 2; ++bj)
; #pragma unroll
;                     for (int n = 0; n < 2; ++n) { const size_t o = (size_t)row * 1024 + u.pn * 256 + bj * 128 + wc * 32 + 8 * fq + 4 * n;
;                         *(f32x4*)(X + o) = *(const f32x4*)(xin + o) + g[bj][n] * acc[ai][bj][m][n]; } }
.LBB0_1926:
	s_ashr_i32 s10, s53, 3
	s_mul_hi_i32 s11, s10, 0x18000
	s_mul_i32 s10, s10, 0x18000
	s_add_u32 s14, s33, s10
	s_addc_u32 s15, s39, s11
	s_lshl_b32 s10, s54, 8
	s_ashr_i32 s11, s10, 31
	s_lshl_b64 s[12:13], s[10:11], 2
	s_add_u32 s12, s14, s12
	s_addc_u32 s13, s15, s13
	v_lshl_add_u32 v162, s53, 8, v164
	s_add_u32 s12, s12, s44
	v_ashrrev_i32_e32 v163, 31, v162
	s_addc_u32 s13, s13, 0
	s_or_b64 s[10:11], s[10:11], s[56:57]
	v_lshlrev_b64 v[146:147], 12, v[162:163]
	s_lshl_b64 s[10:11], s[10:11], 2
	v_add_u32_e32 v168, v146, v96
	v_add_u32_e32 v168, s10, v168
	global_load_dwordx4 v[84:87], v96, s[12:13] offset:16
	global_load_dwordx4 v[92:95], v96, s[12:13]
	global_load_dwordx4 v[40:43], v96, s[12:13] offset:528
	global_load_dwordx4 v[44:47], v96, s[12:13] offset:512
	s_and_b64 vcc, exec, s[6:7]
	s_mov_b32 s46, 0xe00000
	s_mov_b32 s60, 0x1000000
	s_mov_b32 s70, 0x1200000
	s_mov_b32 s71, 0x1400000
	v_add_u32_e32 v169, 0x10000, v168
	v_add_u32_e32 v170, 0x20000, v168
	v_add_u32_e32 v171, 0x30000, v168
	v_add_u32_e32 v172, 0x80000, v168
	v_add_u32_e32 v173, 0x90000, v168
	v_add_u32_e32 v174, 0xa0000, v168
	v_add_u32_e32 v175, 0xb0000, v168
	global_load_dwordx4 v[198:201], v168, s[24:25]
	global_load_dwordx4 v[202:205], v168, s[24:25] offset:16
	global_load_dwordx4 v[206:209], v168, s[24:25] offset:512
	global_load_dwordx4 v[210:213], v168, s[24:25] offset:528
	global_load_dwordx4 v[214:217], v169, s[24:25]
	global_load_dwordx4 v[218:221], v169, s[24:25] offset:16
	global_load_dwordx4 v[222:225], v169, s[24:25] offset:512
	global_load_dwordx4 v[226:229], v169, s[24:25] offset:528
	global_load_dwordx4 v[230:233], v170, s[24:25]
	global_load_dwordx4 v[234:237], v170, s[24:25] offset:16
	global_load_dwordx4 v[238:241], v170, s[24:25] offset:512
	global_load_dwordx4 v[242:245], v170, s[24:25] offset:528
	global_load_dwordx4 v[246:249], v171, s[24:25]
	global_load_dwordx4 v[250:253], v171, s[24:25] offset:16
	global_load_dwordx4 v[182:185], v171, s[24:25] offset:512
	global_load_dwordx4 v[186:189], v171, s[24:25] offset:528
	s_waitcnt vmcnt(12)
	v_pk_fma_f32 v[144:145], v[144:145], v[94:95], v[200:201]
	v_pk_fma_f32 v[142:143], v[142:143], v[92:93], v[198:199]
	v_pk_fma_f32 v[140:141], v[140:141], v[86:87], v[204:205]
	v_pk_fma_f32 v[138:139], v[138:139], v[84:85], v[202:203]
	v_pk_fma_f32 v[136:137], v[136:137], v[46:47], v[208:209]
	v_pk_fma_f32 v[134:135], v[134:135], v[44:45], v[206:207]
	v_pk_fma_f32 v[132:133], v[132:133], v[42:43], v[212:213]
	v_pk_fma_f32 v[130:131], v[130:131], v[40:41], v[210:211]
	global_store_dwordx4 v168, v[142:145], s[24:25]
	global_store_dwordx4 v168, v[138:141], s[24:25] offset:16
	global_store_dwordx4 v168, v[134:137], s[24:25] offset:512
	global_store_dwordx4 v168, v[130:133], s[24:25] offset:528
	global_load_dwordx4 v[198:201], v172, s[24:25]
	global_load_dwordx4 v[202:205], v172, s[24:25] offset:16
	global_load_dwordx4 v[206:209], v172, s[24:25] offset:512
	global_load_dwordx4 v[210:213], v172, s[24:25] offset:528
	s_waitcnt vmcnt(16)
	v_pk_fma_f32 v[128:129], v[128:129], v[94:95], v[216:217]
	v_pk_fma_f32 v[126:127], v[126:127], v[92:93], v[214:215]
	v_pk_fma_f32 v[124:125], v[124:125], v[86:87], v[220:221]
	v_pk_fma_f32 v[122:123], v[122:123], v[84:85], v[218:219]
	v_pk_fma_f32 v[120:121], v[120:121], v[46:47], v[224:225]
	v_pk_fma_f32 v[118:119], v[118:119], v[44:45], v[222:223]
	v_pk_fma_f32 v[116:117], v[116:117], v[42:43], v[228:229]
	v_pk_fma_f32 v[114:115], v[114:115], v[40:41], v[226:227]
	global_store_dwordx4 v169, v[126:129], s[24:25]
	global_store_dwordx4 v169, v[122:125], s[24:25] offset:16
	global_store_dwordx4 v169, v[118:121], s[24:25] offset:512
	global_store_dwordx4 v169, v[114:117], s[24:25] offset:528
	global_load_dwordx4 v[214:217], v173, s[24:25]
	global_load_dwordx4 v[218:221], v173, s[24:25] offset:16
	global_load_dwordx4 v[222:225], v173, s[24:25] offset:512
	global_load_dwordx4 v[226:229], v173, s[24:25] offset:528
	s_waitcnt vmcnt(20)
; #define PG8_BAR __builtin_amdgcn_s_barrier()
;     __device__ __forceinline__ void operator()(const f32x4 (&acc)[2][2][4][2], const Unit& u, int wr, int wc, int fr, int fq) const {
;     ...
; #pragma unroll
;         for (int ai = 0; ai < 2; ++ai)
; #pragma unroll
;             for (int m = 0; m < 4; ++m) { const int row = u.pm * 256 + ai * 128 + wr * 64 + m * 16 + fr;
; #pragma unroll
;                 for (int bj = 0; bj < 2; ++bj)
; #pragma unroll
;                     for (int n = 0; n < 2; ++n) { const size_t o = (size_t)row * 1024 + u.pn * 256 + bj * 128 + wc * 32 + 8 * fq + 4 * n;
;                         *(f32x4*)(X + o) = *(const f32x4*)(xin + o) + g[bj][n] * acc[ai][bj][m][n]; } }
; template <class Epi, class Sched, bool ALIGN_EPI = false, bool SP2 = false>
; __device__ __forceinline__ void gemm_phase(PG8_LAS unsigned char* lds, const Gemm g, const Sched& S, const Epi& E, const int tid_in) {
;     ...
;         if constexpr (!Epi::AFTER_DRAIN) { E(acc, cur, wr, wc, fr, fq); S.done(cur); }
;         if (!has_next) break;
; #pragma unroll
;         for (int a = 0; a < 2; ++a)
; #pragma unroll
;             for (int b = 0; b < 2; ++b)
; #pragma unroll
;                 for (int m = 0; m < 4; ++m)
; #pragma unroll
;                     for (int n = 0; n < 2; ++n) acc[a][b][m][n] = (f32x4){0.f, 0.f, 0.f, 0.f};
;         cur = nxt; cA = nA; cB = nB; ++ui;
;         if constexpr (ALIGN_EPI) { if (wr == 1) PG8_BAR; }
	v_pk_fma_f32 v[112:113], v[112:113], v[94:95], v[232:233]
	v_pk_fma_f32 v[110:111], v[110:111], v[92:93], v[230:231]
	v_pk_fma_f32 v[108:109], v[108:109], v[86:87], v[236:237]
	v_pk_fma_f32 v[106:107], v[106:107], v[84:85], v[234:235]
	v_pk_fma_f32 v[104:105], v[104:105], v[46:47], v[240:241]
	v_pk_fma_f32 v[102:103], v[102:103], v[44:45], v[238:239]
	v_pk_fma_f32 v[100:101], v[100:101], v[42:43], v[244:245]
	v_pk_fma_f32 v[98:99], v[98:99], v[40:41], v[242:243]
	global_store_dwordx4 v170, v[110:113], s[24:25]
	global_store_dwordx4 v170, v[106:109], s[24:25] offset:16
	global_store_dwordx4 v170, v[102:105], s[24:25] offset:512
	global_store_dwordx4 v170, v[98:101], s[24:25] offset:528
	global_load_dwordx4 v[230:233], v174, s[24:25]
	global_load_dwordx4 v[234:237], v174, s[24:25] offset:16
	global_load_dwordx4 v[238:241], v174, s[24:25] offset:512
	global_load_dwordx4 v[242:245], v174, s[24:25] offset:528
	s_waitcnt vmcnt(24)
	v_pk_fma_f32 v[90:91], v[90:91], v[94:95], v[248:249]
	v_pk_fma_f32 v[88:89], v[88:89], v[92:93], v[246:247]
	v_pk_fma_f32 v[82:83], v[82:83], v[86:87], v[252:253]
	v_pk_fma_f32 v[80:81], v[80:81], v[84:85], v[250:251]
	v_pk_fma_f32 v[78:79], v[78:79], v[46:47], v[184:185]
	v_pk_fma_f32 v[76:77], v[76:77], v[44:45], v[182:183]
	v_pk_fma_f32 v[74:75], v[74:75], v[42:43], v[188:189]
	v_pk_fma_f32 v[72:73], v[72:73], v[40:41], v[186:187]
	global_store_dwordx4 v171, v[88:91], s[24:25]
	global_store_dwordx4 v171, v[80:83], s[24:25] offset:16
	global_store_dwordx4 v171, v[76:79], s[24:25] offset:512
	global_store_dwordx4 v171, v[72:75], s[24:25] offset:528
	global_load_dwordx4 v[246:249], v175, s[24:25]
	global_load_dwordx4 v[250:253], v175, s[24:25] offset:16
	global_load_dwordx4 v[182:185], v175, s[24:25] offset:512
	global_load_dwordx4 v[186:189], v175, s[24:25] offset:528
	s_waitcnt vmcnt(24)
	v_pk_fma_f32 v[70:71], v[70:71], v[94:95], v[200:201]
	v_pk_fma_f32 v[68:69], v[68:69], v[92:93], v[198:199]
	v_pk_fma_f32 v[66:67], v[66:67], v[86:87], v[204:205]
	v_pk_fma_f32 v[64:65], v[64:65], v[84:85], v[202:203]
	v_pk_fma_f32 v[62:63], v[62:63], v[46:47], v[208:209]
	v_pk_fma_f32 v[60:61], v[60:61], v[44:45], v[206:207]
	v_pk_fma_f32 v[58:59], v[58:59], v[42:43], v[212:213]
	v_pk_fma_f32 v[56:57], v[56:57], v[40:41], v[210:211]
	global_store_dwordx4 v172, v[68:71], s[24:25]
	global_store_dwordx4 v172, v[64:67], s[24:25] offset:16
	global_store_dwordx4 v172, v[60:63], s[24:25] offset:512
	global_store_dwordx4 v172, v[56:59], s[24:25] offset:528
	s_waitcnt vmcnt(20)
	v_pk_fma_f32 v[54:55], v[54:55], v[94:95], v[216:217]
	v_pk_fma_f32 v[52:53], v[52:53], v[92:93], v[214:215]
	v_pk_fma_f32 v[50:51], v[50:51], v[86:87], v[220:221]
	v_pk_fma_f32 v[48:49], v[48:49], v[84:85], v[218:219]
	v_pk_fma_f32 v[38:39], v[38:39], v[46:47], v[224:225]
	v_pk_fma_f32 v[36:37], v[36:37], v[44:45], v[222:223]
	v_pk_fma_f32 v[34:35], v[34:35], v[42:43], v[228:229]
	v_pk_fma_f32 v[32:33], v[32:33], v[40:41], v[226:227]
	global_store_dwordx4 v173, v[52:55], s[24:25]
	global_store_dwordx4 v173, v[48:51], s[24:25] offset:16
	global_store_dwordx4 v173, v[36:39], s[24:25] offset:512
	global_store_dwordx4 v173, v[32:35], s[24:25] offset:528
	s_waitcnt vmcnt(16)
	v_pk_fma_f32 v[30:31], v[30:31], v[94:95], v[232:233]
	v_pk_fma_f32 v[28:29], v[28:29], v[92:93], v[230:231]
	v_pk_fma_f32 v[26:27], v[26:27], v[86:87], v[236:237]
	v_pk_fma_f32 v[24:25], v[24:25], v[84:85], v[234:235]
	v_pk_fma_f32 v[22:23], v[22:23], v[46:47], v[240:241]
	v_pk_fma_f32 v[20:21], v[20:21], v[44:45], v[238:239]
	v_pk_fma_f32 v[18:19], v[18:19], v[42:43], v[244:245]
	v_pk_fma_f32 v[16:17], v[16:17], v[40:41], v[242:243]
	global_store_dwordx4 v174, v[28:31], s[24:25]
	global_store_dwordx4 v174, v[24:27], s[24:25] offset:16
	global_store_dwordx4 v174, v[20:23], s[24:25] offset:512
	global_store_dwordx4 v174, v[16:19], s[24:25] offset:528
	s_waitcnt vmcnt(12)
	v_pk_fma_f32 v[14:15], v[14:15], v[94:95], v[248:249]
	v_pk_fma_f32 v[12:13], v[12:13], v[92:93], v[246:247]
	v_pk_fma_f32 v[10:11], v[10:11], v[86:87], v[252:253]
	v_pk_fma_f32 v[8:9], v[8:9], v[84:85], v[250:251]
	v_pk_fma_f32 v[6:7], v[6:7], v[46:47], v[184:185]
	v_pk_fma_f32 v[4:5], v[4:5], v[44:45], v[182:183]
	v_pk_fma_f32 v[2:3], v[2:3], v[42:43], v[188:189]
	v_pk_fma_f32 v[0:1], v[0:1], v[40:41], v[186:187]
	global_store_dwordx4 v175, v[12:15], s[24:25]
	global_store_dwordx4 v175, v[8:11], s[24:25] offset:16
	global_store_dwordx4 v175, v[4:7], s[24:25] offset:512
	global_store_dwordx4 v175, v[0:3], s[24:25] offset:528
	s_mov_b64 s[10:11], -1
	s_cbranch_vccnz .LBB0_1911
	s_andn2_b64 vcc, exec, s[0:1]
	s_cbranch_vccnz .LBB0_1910
	s_barrier
	s_branch .LBB0_1910
